# p4 + non-temporal hint on the big streaming output stores of the in-projection/up GEMMs (E1, O1, M1): outputs are read only in a later phase
# baseline (speedup 1.0000x reference)
.Lalign_skip_0:
	v_pk_mul_f32 v[122:123], v[122:123], v[0:1] op_sel_hi:[1,0]
	v_add_f32_e32 v153, v153, v154
	v_mul_f32_e32 v178, 0x3d372713, v122
	v_add_f32_e32 v152, v152, v153
	v_mul_f32_e32 v177, 0x3fcc422a, v122
	v_fma_f32 v178, v122, v178, 1.0
	v_add_f32_e32 v151, v151, v152
	v_mul_f32_e32 v177, v177, v178
	v_mov_b32_e32 v152, v151
	v_mul_f32_e32 v177, 0xbfb8aa3b, v177
	s_nop 0
	v_permlane16_swap_b32_e32 v151, v152
	v_exp_f32_e32 v177, v177
	v_add_f32_e32 v175, v151, v152
	ds_read_b128 v[152:155], v167 offset:2048
	v_mul_f32_e32 v178, 0x3d372713, v123
	v_add_f32_e32 v177, 1.0, v177
	v_rcp_f32_e32 v177, v177
	v_fma_f32 v178, v123, v178, 1.0
	s_waitcnt lgkmcnt(0)
	v_lshlrev_b32_e32 v151, 16, v152
	v_and_b32_e32 v152, 0xffff0000, v152
	v_add_f32_e32 v151, v151, v152
	v_lshlrev_b32_e32 v152, 16, v153
	v_and_b32_e32 v153, 0xffff0000, v153
	v_add_f32_e32 v152, v152, v153
	v_add_f32_e32 v151, v151, v152
	v_lshlrev_b32_e32 v152, 16, v154
	v_and_b32_e32 v153, 0xffff0000, v154
	v_mul_f32_e32 v122, v122, v177
	v_mul_f32_e32 v177, 0x3fcc422a, v123
	v_add_f32_e32 v152, v152, v153
	v_lshlrev_b32_e32 v153, 16, v155
	v_and_b32_e32 v154, 0xffff0000, v155
	v_mul_f32_e32 v177, v177, v178
	v_add_f32_e32 v153, v153, v154
	v_mul_f32_e32 v177, 0xbfb8aa3b, v177
	v_add_f32_e32 v152, v152, v153
	v_exp_f32_e32 v177, v177
	v_add_f32_e32 v151, v151, v152
	v_mov_b32_e32 v152, v151
	s_nop 1
	v_permlane16_swap_b32_e32 v151, v152
	v_add_f32_e32 v173, v151, v152
	ds_read_b128 v[152:155], v167 offset:3072
	v_add_f32_e32 v177, 1.0, v177
	v_rcp_f32_e32 v177, v177
	v_pk_mul_f32 v[124:125], v[124:125], v[0:1] op_sel_hi:[1,0]
	v_pk_mul_f32 v[126:127], v[126:127], v[0:1] op_sel_hi:[1,0]
	v_mul_f32_e32 v178, 0x3d372713, v124
	s_waitcnt lgkmcnt(0)
	v_lshlrev_b32_e32 v151, 16, v152
	v_and_b32_e32 v152, 0xffff0000, v152
	v_mul_f32_e32 v123, v123, v177
	v_mul_f32_e32 v177, 0x3fcc422a, v124
	v_fma_f32 v178, v124, v178, 1.0
	v_add_f32_e32 v151, v151, v152
	v_lshlrev_b32_e32 v152, 16, v153
	v_and_b32_e32 v153, 0xffff0000, v153
	v_mul_f32_e32 v177, v177, v178
	v_add_f32_e32 v152, v152, v153
	v_mul_f32_e32 v177, 0xbfb8aa3b, v177
	v_add_f32_e32 v151, v151, v152
	v_lshlrev_b32_e32 v152, 16, v154
	v_and_b32_e32 v153, 0xffff0000, v154
	v_exp_f32_e32 v177, v177
	v_add_f32_e32 v152, v152, v153
	v_lshlrev_b32_e32 v153, 16, v155
	v_and_b32_e32 v154, 0xffff0000, v155
	v_add_f32_e32 v153, v153, v154
	v_add_f32_e32 v152, v152, v153
	v_add_f32_e32 v151, v151, v152
	v_add_f32_e32 v177, 1.0, v177
	v_mov_b32_e32 v152, v151
	v_rcp_f32_e32 v177, v177
	s_nop 0
	v_permlane16_swap_b32_e32 v151, v152
	v_add_f32_e32 v171, v151, v152
	ds_read_b128 v[152:155], v167 offset:8192
	v_mul_f32_e32 v178, 0x3d372713, v125
	v_mul_f32_e32 v124, v124, v177
	v_mul_f32_e32 v177, 0x3fcc422a, v125
	v_fma_f32 v178, v125, v178, 1.0
	v_mul_f32_e32 v177, v177, v178
	v_mul_f32_e32 v177, 0xbfb8aa3b, v177
	s_waitcnt lgkmcnt(0)
	v_lshlrev_b32_e32 v151, 16, v152
	v_and_b32_e32 v152, 0xffff0000, v152
	v_exp_f32_e32 v177, v177
	v_add_f32_e32 v151, v151, v152
	v_lshlrev_b32_e32 v152, 16, v153
	v_and_b32_e32 v153, 0xffff0000, v153
	v_add_f32_e32 v152, v152, v153
	v_add_f32_e32 v151, v151, v152
	v_lshlrev_b32_e32 v152, 16, v154
	v_and_b32_e32 v153, 0xffff0000, v154
	v_add_f32_e32 v152, v152, v153
	v_lshlrev_b32_e32 v153, 16, v155
	v_and_b32_e32 v154, 0xffff0000, v155
	v_add_f32_e32 v177, 1.0, v177
	v_add_f32_e32 v153, v153, v154
	v_rcp_f32_e32 v177, v177
	v_add_f32_e32 v152, v152, v153
	v_add_f32_e32 v151, v151, v152
	v_mov_b32_e32 v152, v151
	v_mul_f32_e32 v178, 0x3d372713, v126
	s_nop 0
	v_permlane16_swap_b32_e32 v151, v152
	v_mul_f32_e32 v125, v125, v177
	v_mul_f32_e32 v177, 0x3fcc422a, v126
	v_fma_f32 v178, v126, v178, 1.0
	v_add_f32_e32 v169, v151, v152
	ds_read_b128 v[152:155], v167 offset:9216
	v_mul_f32_e32 v177, v177, v178
	v_mul_f32_e32 v177, 0xbfb8aa3b, v177
	v_exp_f32_e32 v177, v177
	v_mul_f32_e32 v178, 0x3d372713, v127
	s_waitcnt lgkmcnt(0)
	v_lshlrev_b32_e32 v151, 16, v152
	v_and_b32_e32 v152, 0xffff0000, v152
	v_add_f32_e32 v151, v151, v152
	v_lshlrev_b32_e32 v152, 16, v153
	v_and_b32_e32 v153, 0xffff0000, v153
	v_add_f32_e32 v177, 1.0, v177
	v_add_f32_e32 v152, v152, v153
	v_rcp_f32_e32 v177, v177
	v_add_f32_e32 v151, v151, v152
	v_lshlrev_b32_e32 v152, 16, v154
	v_and_b32_e32 v153, 0xffff0000, v154
	v_add_f32_e32 v152, v152, v153
	v_lshlrev_b32_e32 v153, 16, v155
	v_and_b32_e32 v154, 0xffff0000, v155
	v_add_f32_e32 v153, v153, v154
	v_add_f32_e32 v152, v152, v153
	v_mul_f32_e32 v126, v126, v177
	v_mul_f32_e32 v177, 0x3fcc422a, v127
	v_fma_f32 v178, v127, v178, 1.0
	v_add_f32_e32 v151, v151, v152
	v_mul_f32_e32 v177, v177, v178
	v_mov_b32_e32 v152, v151
	v_mul_f32_e32 v177, 0xbfb8aa3b, v177
	s_nop 0
	v_permlane16_swap_b32_e32 v151, v152
	v_exp_f32_e32 v177, v177
	v_add_f32_e32 v161, v151, v152
	ds_read_b128 v[152:155], v167 offset:10240
	v_pk_mul_f32 v[128:129], v[128:129], v[0:1] op_sel_hi:[1,0]
	v_add_f32_e32 v177, 1.0, v177
	v_rcp_f32_e32 v177, v177
	v_mul_f32_e32 v178, 0x3d372713, v128
	s_waitcnt lgkmcnt(0)
	v_lshlrev_b32_e32 v151, 16, v152
	v_and_b32_e32 v152, 0xffff0000, v152
	v_add_f32_e32 v151, v151, v152
	v_lshlrev_b32_e32 v152, 16, v153
	v_and_b32_e32 v153, 0xffff0000, v153
	v_add_f32_e32 v152, v152, v153
	v_add_f32_e32 v151, v151, v152
	v_lshlrev_b32_e32 v152, 16, v154
	v_and_b32_e32 v153, 0xffff0000, v154
	v_mul_f32_e32 v127, v127, v177
	v_mul_f32_e32 v177, 0x3fcc422a, v128
	v_fma_f32 v178, v128, v178, 1.0
	v_add_f32_e32 v152, v152, v153
	v_lshlrev_b32_e32 v153, 16, v155
	v_and_b32_e32 v154, 0xffff0000, v155
	v_mul_f32_e32 v177, v177, v178
	v_add_f32_e32 v153, v153, v154
	v_mul_f32_e32 v177, 0xbfb8aa3b, v177
	v_add_f32_e32 v152, v152, v153
	v_exp_f32_e32 v177, v177
	v_add_f32_e32 v151, v151, v152
	v_mov_b32_e32 v152, v151
	s_nop 1
	v_permlane16_swap_b32_e32 v151, v152
	v_add_f32_e32 v159, v151, v152
	ds_read_b128 v[152:155], v167 offset:11264
	v_add_f32_e32 v177, 1.0, v177
	v_rcp_f32_e32 v177, v177
	v_mul_f32_e32 v178, 0x3d372713, v129
	v_fma_f32 v178, v129, v178, 1.0
	s_waitcnt lgkmcnt(0)
	v_lshlrev_b32_e32 v151, 16, v152
	v_and_b32_e32 v152, 0xffff0000, v152
	v_mul_f32_e32 v128, v128, v177
	v_mul_f32_e32 v177, 0x3fcc422a, v129
	v_add_f32_e32 v151, v151, v152
	v_lshlrev_b32_e32 v152, 16, v153
	v_and_b32_e32 v153, 0xffff0000, v153
	v_mul_f32_e32 v177, v177, v178
	v_add_f32_e32 v152, v152, v153
	v_mul_f32_e32 v177, 0xbfb8aa3b, v177
	v_add_f32_e32 v151, v151, v152
	v_lshlrev_b32_e32 v152, 16, v154
	v_and_b32_e32 v153, 0xffff0000, v154
	v_exp_f32_e32 v177, v177
	v_add_f32_e32 v152, v152, v153
	v_lshlrev_b32_e32 v153, 16, v155
	v_and_b32_e32 v154, 0xffff0000, v155
	v_add_f32_e32 v153, v153, v154
	v_add_f32_e32 v152, v152, v153
	v_add_f32_e32 v151, v151, v152
	v_add_f32_e32 v177, 1.0, v177
	v_mov_b32_e32 v152, v151
	v_rcp_f32_e32 v177, v177
	s_nop 0
	v_permlane16_swap_b32_e32 v151, v152
	v_add_f32_e32 v157, v151, v152
	v_lshl_or_b32 v152, s12, 8, v165
	v_ashrrev_i32_e32 v153, 31, v152
	v_ashrrev_i32_e32 v151, 31, v150
	v_lshl_add_u64 v[152:153], v[152:153], 1, v[140:141]
	v_lshlrev_b64 v[154:155], 13, v[150:151]
	v_mul_f32_e32 v129, v129, v177
	v_mul_f32_e32 v177, v123, v123
	v_lshl_add_u64 v[154:155], v[152:153], 0, v[154:155]
	v_fmac_f32_e32 v177, v122, v122
	v_mul_f32_e32 v178, v125, v125
	v_cvt_pk_bf16_f32 v122, v122, v123
	v_pk_mul_f32 v[114:115], v[114:115], v[0:1] op_sel_hi:[1,0]
	v_fmac_f32_e32 v178, v124, v124
	v_cvt_pk_bf16_f32 v123, v124, v125
	v_cvt_pk_bf16_f32 v124, v126, v127
	v_cvt_pk_bf16_f32 v125, v128, v129
	global_store_dwordx4 v[154:155], v[122:125], off nt
	v_pk_mul_f32 v[116:117], v[116:117], v[0:1] op_sel_hi:[1,0]
	v_pk_mul_f32 v[120:121], v[120:121], v[0:1] op_sel_hi:[1,0]
	v_mul_f32_e32 v122, 0x3d372713, v114
	v_pk_mul_f32 v[118:119], v[118:119], v[0:1] op_sel_hi:[1,0]
	v_mul_f32_e32 v0, 0x3fcc422a, v114
	v_fma_f32 v122, v114, v122, 1.0
	v_mul_f32_e32 v0, v0, v122
	v_mul_f32_e32 v0, 0xbfb8aa3b, v0
	v_exp_f32_e32 v0, v0
	v_mul_f32_e32 v122, 0x3d372713, v115
	v_fma_f32 v122, v115, v122, 1.0
	v_add_f32_e32 v177, v177, v178
	v_add_f32_e32 v0, 1.0, v0
	v_rcp_f32_e32 v0, v0
	v_mul_f32_e32 v178, v127, v127
	v_mul_f32_e32 v179, v129, v129
	v_fmac_f32_e32 v178, v126, v126
	v_mul_f32_e32 v0, v114, v0
	v_mul_f32_e32 v114, 0x3fcc422a, v115
	v_mul_f32_e32 v114, v114, v122
	v_mul_f32_e32 v114, 0xbfb8aa3b, v114
	v_exp_f32_e32 v114, v114
	v_mul_f32_e32 v122, 0x3d372713, v116
	v_fma_f32 v122, v116, v122, 1.0
	v_fmac_f32_e32 v179, v128, v128
	v_add_f32_e32 v114, 1.0, v114
	v_rcp_f32_e32 v114, v114
	v_add_f32_e32 v178, v178, v179
	v_add_f32_e32 v177, v177, v178
	v_mov_b32_e32 v176, v175
	v_mul_f32_e32 v114, v115, v114
	v_mul_f32_e32 v115, 0x3fcc422a, v116
	v_mul_f32_e32 v115, v115, v122
	v_mul_f32_e32 v115, 0xbfb8aa3b, v115
	v_exp_f32_e32 v115, v115
	v_mul_f32_e32 v122, 0x3d372713, v117
	v_fma_f32 v122, v117, v122, 1.0
	v_mov_b32_e32 v174, v173
	v_add_f32_e32 v115, 1.0, v115
	v_rcp_f32_e32 v115, v115
	v_mov_b32_e32 v172, v171
	v_mov_b32_e32 v170, v169
	v_mov_b32_e32 v168, v161
	v_mul_f32_e32 v115, v116, v115
	v_mul_f32_e32 v116, 0x3fcc422a, v117
	v_mul_f32_e32 v116, v116, v122
	v_mul_f32_e32 v116, 0xbfb8aa3b, v116
	v_exp_f32_e32 v116, v116
	v_mul_f32_e32 v122, 0x3d372713, v118
	v_fma_f32 v122, v118, v122, 1.0
	v_mov_b32_e32 v160, v159
	v_add_f32_e32 v116, 1.0, v116
	v_rcp_f32_e32 v116, v116
	v_mov_b32_e32 v158, v157
	v_permlane32_swap_b32_e32 v175, v176
	v_mul_f32_e32 v116, v117, v116
	v_mul_f32_e32 v117, 0x3fcc422a, v118
	v_mul_f32_e32 v117, v117, v122
	v_mul_f32_e32 v117, 0xbfb8aa3b, v117
	v_exp_f32_e32 v117, v117
	v_mul_f32_e32 v122, 0x3d372713, v119
	v_fma_f32 v122, v119, v122, 1.0
	v_permlane32_swap_b32_e32 v173, v174
	v_add_f32_e32 v117, 1.0, v117
	v_rcp_f32_e32 v117, v117
	v_permlane32_swap_b32_e32 v171, v172
	v_permlane32_swap_b32_e32 v169, v170
	v_mul_f32_e32 v117, v118, v117
	v_mul_f32_e32 v118, 0x3fcc422a, v119
	v_mul_f32_e32 v118, v118, v122
	v_mul_f32_e32 v118, 0xbfb8aa3b, v118
	v_exp_f32_e32 v118, v118
	v_mul_f32_e32 v122, 0x3d372713, v120
	v_fma_f32 v122, v120, v122, 1.0
	v_permlane32_swap_b32_e32 v161, v168
	v_add_f32_e32 v118, 1.0, v118
	v_rcp_f32_e32 v118, v118
	v_permlane32_swap_b32_e32 v159, v160
	v_permlane32_swap_b32_e32 v157, v158
	v_mul_f32_e32 v118, v119, v118
	v_mul_f32_e32 v119, 0x3fcc422a, v120
	v_mul_f32_e32 v119, v119, v122
	v_mul_f32_e32 v119, 0xbfb8aa3b, v119
	v_exp_f32_e32 v119, v119
	v_mul_f32_e32 v122, 0x3d372713, v121
	v_fma_f32 v122, v121, v122, 1.0
	v_add_f32_e32 v119, 1.0, v119
	v_rcp_f32_e32 v119, v119
	s_nop 0
	v_mul_f32_e32 v119, v120, v119
	v_mul_f32_e32 v120, 0x3fcc422a, v121
	v_mul_f32_e32 v120, v120, v122
	v_mul_f32_e32 v120, 0xbfb8aa3b, v120
	v_exp_f32_e32 v120, v120
	v_mul_f32_e32 v122, v116, v116
	v_fmac_f32_e32 v122, v115, v115
	v_add_f32_e32 v120, 1.0, v120
	v_rcp_f32_e32 v120, v120
	s_nop 0
	v_mul_f32_e32 v120, v121, v120
	v_mul_f32_e32 v121, v114, v114
	v_fmac_f32_e32 v121, v0, v0
	v_add_f32_e32 v121, v121, v122
	v_mul_f32_e32 v122, v118, v118
	v_mul_f32_e32 v123, v120, v120
	v_fmac_f32_e32 v122, v117, v117
	v_fmac_f32_e32 v123, v119, v119
	v_add_f32_e32 v122, v122, v123
	v_add_f32_e32 v121, v121, v122
	v_add_f32_e32 v121, v177, v121
	v_cvt_pk_bf16_f32 v114, v0, v114
	v_mov_b32_e32 v0, v121
	s_nop 1
	v_permlane16_swap_b32_e32 v121, v0
	v_add_f32_e32 v0, v121, v0
	v_cvt_pk_bf16_f32 v115, v115, v116
	v_cvt_pk_bf16_f32 v116, v117, v118
	v_cvt_pk_bf16_f32 v117, v119, v120
	global_store_dwordx4 v[154:155], v[114:117], off offset:256 nt
	s_nop 1
	v_mov_b32_e32 v114, v0
	s_nop 1
	v_permlane32_swap_b32_e32 v0, v114
	s_and_saveexec_b64 s[0:1], s[2:3]
	s_cbranch_execz .LBB0_175
	v_add_f32_e32 v0, v0, v114
	v_lshlrev_b64 v[114:115], 7, v[150:151]
	s_lshl_b32 s36, s12, 2
	v_lshl_add_u64 v[114:115], v[138:139], 0, v[114:115]
	s_mov_b32 s37, s40
	v_lshl_add_u64 v[114:115], s[36:37], 2, v[114:115]
	s_lshl_b32 s36, s28, 2
	v_lshl_add_u64 v[114:115], v[114:115], 0, s[36:37]
	global_store_dword v[114:115], v0, off offset:-128
.LBB0_175:
	s_or_b64 exec, exec, s[0:1]
	v_add_f32_e32 v0, v175, v176
	v_fmamk_f32 v0, v0, 0x3a000000, v240
	v_rsq_f32_e32 v0, v0
	v_or_b32_e32 v114, 16, v150
	v_ashrrev_i32_e32 v115, 31, v114
	v_lshlrev_b64 v[116:117], 13, v[114:115]
	v_pk_mul_f32 v[106:107], v[106:107], v[0:1] op_sel_hi:[1,0]
	v_pk_mul_f32 v[108:109], v[108:109], v[0:1] op_sel_hi:[1,0]
	v_mul_f32_e32 v119, 0x3d372713, v106
	v_mul_f32_e32 v118, 0x3fcc422a, v106
	v_fma_f32 v119, v106, v119, 1.0
	v_mul_f32_e32 v118, v118, v119
	v_mul_f32_e32 v118, 0xbfb8aa3b, v118
	v_exp_f32_e32 v118, v118
	v_mul_f32_e32 v119, 0x3d372713, v107
	v_fma_f32 v119, v107, v119, 1.0
	v_pk_mul_f32 v[110:111], v[110:111], v[0:1] op_sel_hi:[1,0]
	v_add_f32_e32 v118, 1.0, v118
	v_rcp_f32_e32 v118, v118
	v_pk_mul_f32 v[112:113], v[112:113], v[0:1] op_sel_hi:[1,0]
	v_lshl_add_u64 v[116:117], v[152:153], 0, v[116:117]
	v_pk_mul_f32 v[98:99], v[98:99], v[0:1] op_sel_hi:[1,0]
	v_mul_f32_e32 v106, v106, v118
	v_mul_f32_e32 v118, 0x3fcc422a, v107
	v_mul_f32_e32 v118, v118, v119
	v_mul_f32_e32 v118, 0xbfb8aa3b, v118
	v_exp_f32_e32 v118, v118
	v_mul_f32_e32 v119, 0x3d372713, v108
	v_fma_f32 v119, v108, v119, 1.0
	v_pk_mul_f32 v[100:101], v[100:101], v[0:1] op_sel_hi:[1,0]
	v_add_f32_e32 v118, 1.0, v118
	v_rcp_f32_e32 v118, v118
	v_pk_mul_f32 v[104:105], v[104:105], v[0:1] op_sel_hi:[1,0]
	v_pk_mul_f32 v[102:103], v[102:103], v[0:1] op_sel_hi:[1,0]
	v_mul_f32_e32 v0, 0x3fcc422a, v98
	v_mul_f32_e32 v107, v107, v118
	v_mul_f32_e32 v118, 0x3fcc422a, v108
	v_mul_f32_e32 v118, v118, v119
	v_mul_f32_e32 v118, 0xbfb8aa3b, v118
	v_exp_f32_e32 v118, v118
	v_mul_f32_e32 v119, 0x3d372713, v109
	v_fma_f32 v119, v109, v119, 1.0
	v_add_f32_e32 v118, 1.0, v118
	v_rcp_f32_e32 v118, v118
	s_nop 0
	v_mul_f32_e32 v108, v108, v118
	v_mul_f32_e32 v118, 0x3fcc422a, v109
	v_mul_f32_e32 v118, v118, v119
	v_mul_f32_e32 v118, 0xbfb8aa3b, v118
	v_exp_f32_e32 v118, v118
	v_mul_f32_e32 v119, 0x3d372713, v110
	v_fma_f32 v119, v110, v119, 1.0
	v_add_f32_e32 v118, 1.0, v118
	v_rcp_f32_e32 v118, v118
	s_nop 0
	v_mul_f32_e32 v109, v109, v118
	v_mul_f32_e32 v118, 0x3fcc422a, v110
	v_mul_f32_e32 v118, v118, v119
	v_mul_f32_e32 v118, 0xbfb8aa3b, v118
	v_exp_f32_e32 v118, v118
	v_mul_f32_e32 v119, 0x3d372713, v111
	v_fma_f32 v119, v111, v119, 1.0
	v_add_f32_e32 v118, 1.0, v118
	v_rcp_f32_e32 v118, v118
	s_nop 0
	v_mul_f32_e32 v110, v110, v118
	v_mul_f32_e32 v118, 0x3fcc422a, v111
	v_mul_f32_e32 v118, v118, v119
	v_mul_f32_e32 v118, 0xbfb8aa3b, v118
	v_exp_f32_e32 v118, v118
	v_mul_f32_e32 v119, 0x3d372713, v112
	v_fma_f32 v119, v112, v119, 1.0
	v_add_f32_e32 v118, 1.0, v118
	v_rcp_f32_e32 v118, v118
	s_nop 0
	v_mul_f32_e32 v111, v111, v118
	v_mul_f32_e32 v118, 0x3fcc422a, v112
	v_mul_f32_e32 v118, v118, v119
	v_mul_f32_e32 v118, 0xbfb8aa3b, v118
	v_exp_f32_e32 v118, v118
	v_mul_f32_e32 v119, 0x3d372713, v113
	v_fma_f32 v119, v113, v119, 1.0
	v_add_f32_e32 v118, 1.0, v118
	v_rcp_f32_e32 v118, v118
	s_nop 0
	v_mul_f32_e32 v112, v112, v118
	v_mul_f32_e32 v118, 0x3fcc422a, v113
	v_mul_f32_e32 v118, v118, v119
	v_mul_f32_e32 v118, 0xbfb8aa3b, v118
	v_exp_f32_e32 v118, v118
	v_mul_f32_e32 v119, v109, v109
	v_fmac_f32_e32 v119, v108, v108
	v_add_f32_e32 v118, 1.0, v118
	v_rcp_f32_e32 v118, v118
	s_nop 0
	v_mul_f32_e32 v113, v113, v118
	v_mul_f32_e32 v118, v107, v107
	v_fmac_f32_e32 v118, v106, v106
	v_cvt_pk_bf16_f32 v106, v106, v107
	v_cvt_pk_bf16_f32 v107, v108, v109
	v_cvt_pk_bf16_f32 v108, v110, v111
	v_cvt_pk_bf16_f32 v109, v112, v113
	global_store_dwordx4 v[116:117], v[106:109], off nt
	v_add_f32_e32 v118, v118, v119
	v_mul_f32_e32 v119, v111, v111
	v_mul_f32_e32 v106, 0x3d372713, v98
	v_fma_f32 v106, v98, v106, 1.0
	v_mul_f32_e32 v0, v0, v106
	v_mul_f32_e32 v0, 0xbfb8aa3b, v0
	v_exp_f32_e32 v0, v0
	v_mul_f32_e32 v106, 0x3d372713, v99
	v_fma_f32 v106, v99, v106, 1.0
	v_mul_f32_e32 v120, v113, v113
	v_add_f32_e32 v0, 1.0, v0
	v_rcp_f32_e32 v0, v0
	v_fmac_f32_e32 v119, v110, v110
	v_fmac_f32_e32 v120, v112, v112
	v_add_f32_e32 v119, v119, v120
	v_mul_f32_e32 v0, v98, v0
	v_mul_f32_e32 v98, 0x3fcc422a, v99
	v_mul_f32_e32 v98, v98, v106
	v_mul_f32_e32 v98, 0xbfb8aa3b, v98
	v_exp_f32_e32 v98, v98
	v_mul_f32_e32 v106, 0x3d372713, v100
	v_fma_f32 v106, v100, v106, 1.0
	v_add_f32_e32 v118, v118, v119
	v_add_f32_e32 v98, 1.0, v98
	v_rcp_f32_e32 v98, v98
	s_nop 0
	v_mul_f32_e32 v98, v99, v98
	v_mul_f32_e32 v99, 0x3fcc422a, v100
	v_mul_f32_e32 v99, v99, v106
	v_mul_f32_e32 v99, 0xbfb8aa3b, v99
	v_exp_f32_e32 v99, v99
	v_mul_f32_e32 v106, 0x3d372713, v101
	v_fma_f32 v106, v101, v106, 1.0
	v_add_f32_e32 v99, 1.0, v99
	v_rcp_f32_e32 v99, v99
	s_nop 0
	v_mul_f32_e32 v99, v100, v99
	v_mul_f32_e32 v100, 0x3fcc422a, v101
	v_mul_f32_e32 v100, v100, v106
	v_mul_f32_e32 v100, 0xbfb8aa3b, v100
	v_exp_f32_e32 v100, v100
	v_mul_f32_e32 v106, 0x3d372713, v102
	v_fma_f32 v106, v102, v106, 1.0
	v_add_f32_e32 v100, 1.0, v100
	v_rcp_f32_e32 v100, v100
	s_nop 0
	v_mul_f32_e32 v100, v101, v100
	v_mul_f32_e32 v101, 0x3fcc422a, v102
	v_mul_f32_e32 v101, v101, v106
	v_mul_f32_e32 v101, 0xbfb8aa3b, v101
	v_exp_f32_e32 v101, v101
	v_mul_f32_e32 v106, 0x3d372713, v103
	v_fma_f32 v106, v103, v106, 1.0
	v_add_f32_e32 v101, 1.0, v101
	v_rcp_f32_e32 v101, v101
	s_nop 0
	v_mul_f32_e32 v101, v102, v101
	v_mul_f32_e32 v102, 0x3fcc422a, v103
	v_mul_f32_e32 v102, v102, v106
	v_mul_f32_e32 v102, 0xbfb8aa3b, v102
	v_exp_f32_e32 v102, v102
	v_mul_f32_e32 v106, 0x3d372713, v104
	v_fma_f32 v106, v104, v106, 1.0
	v_add_f32_e32 v102, 1.0, v102
	v_rcp_f32_e32 v102, v102
	s_nop 0
	v_mul_f32_e32 v102, v103, v102
	v_mul_f32_e32 v103, 0x3fcc422a, v104
	v_mul_f32_e32 v103, v103, v106
	v_mul_f32_e32 v103, 0xbfb8aa3b, v103
	v_exp_f32_e32 v103, v103
	v_mul_f32_e32 v106, 0x3d372713, v105
	v_fma_f32 v106, v105, v106, 1.0
	v_add_f32_e32 v103, 1.0, v103
	v_rcp_f32_e32 v103, v103
	s_nop 0
	v_mul_f32_e32 v103, v104, v103
	v_mul_f32_e32 v104, 0x3fcc422a, v105
	v_mul_f32_e32 v104, v104, v106
	v_mul_f32_e32 v104, 0xbfb8aa3b, v104
	v_exp_f32_e32 v104, v104
	v_mul_f32_e32 v106, v100, v100
	v_fmac_f32_e32 v106, v99, v99
	v_add_f32_e32 v104, 1.0, v104
	v_rcp_f32_e32 v104, v104
	s_nop 0
	v_mul_f32_e32 v104, v105, v104
	v_mul_f32_e32 v105, v98, v98
	v_fmac_f32_e32 v105, v0, v0
	v_add_f32_e32 v105, v105, v106
	v_mul_f32_e32 v106, v102, v102
	v_mul_f32_e32 v107, v104, v104
	v_fmac_f32_e32 v106, v101, v101
	v_fmac_f32_e32 v107, v103, v103
	v_add_f32_e32 v106, v106, v107
	v_add_f32_e32 v105, v105, v106
	v_add_f32_e32 v105, v118, v105
	v_cvt_pk_bf16_f32 v98, v0, v98
	v_mov_b32_e32 v0, v105
	s_nop 1
	v_permlane16_swap_b32_e32 v105, v0
	v_add_f32_e32 v0, v105, v0
	v_cvt_pk_bf16_f32 v99, v99, v100
	v_cvt_pk_bf16_f32 v100, v101, v102
	v_cvt_pk_bf16_f32 v101, v103, v104
	global_store_dwordx4 v[116:117], v[98:101], off offset:256 nt
	s_nop 1
	v_mov_b32_e32 v98, v0
	s_nop 1
	v_permlane32_swap_b32_e32 v0, v98
	s_and_saveexec_b64 s[0:1], s[2:3]
	s_cbranch_execz .LBB0_177
	v_add_f32_e32 v0, v0, v98
	v_lshlrev_b64 v[98:99], 7, v[114:115]
	s_lshl_b32 s36, s12, 2
	v_lshl_add_u64 v[98:99], v[138:139], 0, v[98:99]
	s_mov_b32 s37, s40
	v_lshl_add_u64 v[98:99], s[36:37], 2, v[98:99]
	s_lshl_b32 s36, s28, 2
	v_lshl_add_u64 v[98:99], v[98:99], 0, s[36:37]
	global_store_dword v[98:99], v0, off offset:-128
.LBB0_177:
	s_or_b64 exec, exec, s[0:1]
	v_add_f32_e32 v0, v173, v174
	v_fmamk_f32 v0, v0, 0x3a000000, v240
	v_rsq_f32_e32 v0, v0
	v_or_b32_e32 v98, 32, v150
	v_ashrrev_i32_e32 v99, 31, v98
	v_lshlrev_b64 v[100:101], 13, v[98:99]
	v_pk_mul_f32 v[90:91], v[90:91], v[0:1] op_sel_hi:[1,0]
	v_pk_mul_f32 v[92:93], v[92:93], v[0:1] op_sel_hi:[1,0]
	v_mul_f32_e32 v103, 0x3d372713, v90
	v_mul_f32_e32 v102, 0x3fcc422a, v90
	v_fma_f32 v103, v90, v103, 1.0
	v_mul_f32_e32 v102, v102, v103
	v_mul_f32_e32 v102, 0xbfb8aa3b, v102
	v_exp_f32_e32 v102, v102
	v_mul_f32_e32 v103, 0x3d372713, v91
	v_fma_f32 v103, v91, v103, 1.0
	v_pk_mul_f32 v[94:95], v[94:95], v[0:1] op_sel_hi:[1,0]
	v_add_f32_e32 v102, 1.0, v102
	v_rcp_f32_e32 v102, v102
	v_pk_mul_f32 v[96:97], v[96:97], v[0:1] op_sel_hi:[1,0]
	v_lshl_add_u64 v[100:101], v[152:153], 0, v[100:101]
	v_pk_mul_f32 v[82:83], v[82:83], v[0:1] op_sel_hi:[1,0]
	v_mul_f32_e32 v90, v90, v102
	v_mul_f32_e32 v102, 0x3fcc422a, v91
	v_mul_f32_e32 v102, v102, v103
	v_mul_f32_e32 v102, 0xbfb8aa3b, v102
	v_exp_f32_e32 v102, v102
	v_mul_f32_e32 v103, 0x3d372713, v92
	v_fma_f32 v103, v92, v103, 1.0
	v_pk_mul_f32 v[84:85], v[84:85], v[0:1] op_sel_hi:[1,0]
	v_add_f32_e32 v102, 1.0, v102
	v_rcp_f32_e32 v102, v102
	v_pk_mul_f32 v[88:89], v[88:89], v[0:1] op_sel_hi:[1,0]
	v_pk_mul_f32 v[86:87], v[86:87], v[0:1] op_sel_hi:[1,0]
	v_mul_f32_e32 v0, 0x3fcc422a, v82
	v_mul_f32_e32 v91, v91, v102
	v_mul_f32_e32 v102, 0x3fcc422a, v92
	v_mul_f32_e32 v102, v102, v103
	v_mul_f32_e32 v102, 0xbfb8aa3b, v102
	v_exp_f32_e32 v102, v102
	v_mul_f32_e32 v103, 0x3d372713, v93
	v_fma_f32 v103, v93, v103, 1.0
	v_add_f32_e32 v102, 1.0, v102
	v_rcp_f32_e32 v102, v102
	s_nop 0
	v_mul_f32_e32 v92, v92, v102
	v_mul_f32_e32 v102, 0x3fcc422a, v93
	v_mul_f32_e32 v102, v102, v103
	v_mul_f32_e32 v102, 0xbfb8aa3b, v102
	v_exp_f32_e32 v102, v102
	v_mul_f32_e32 v103, 0x3d372713, v94
	v_fma_f32 v103, v94, v103, 1.0
	v_add_f32_e32 v102, 1.0, v102
	v_rcp_f32_e32 v102, v102
	s_nop 0
	v_mul_f32_e32 v93, v93, v102
	v_mul_f32_e32 v102, 0x3fcc422a, v94
	v_mul_f32_e32 v102, v102, v103
	v_mul_f32_e32 v102, 0xbfb8aa3b, v102
	v_exp_f32_e32 v102, v102
	v_mul_f32_e32 v103, 0x3d372713, v95
	v_fma_f32 v103, v95, v103, 1.0
	v_add_f32_e32 v102, 1.0, v102
	v_rcp_f32_e32 v102, v102
	s_nop 0
	v_mul_f32_e32 v94, v94, v102
	v_mul_f32_e32 v102, 0x3fcc422a, v95
	v_mul_f32_e32 v102, v102, v103
	v_mul_f32_e32 v102, 0xbfb8aa3b, v102
	v_exp_f32_e32 v102, v102
	v_mul_f32_e32 v103, 0x3d372713, v96
	v_fma_f32 v103, v96, v103, 1.0
	v_add_f32_e32 v102, 1.0, v102
	v_rcp_f32_e32 v102, v102
	s_nop 0
	v_mul_f32_e32 v95, v95, v102
	v_mul_f32_e32 v102, 0x3fcc422a, v96
	v_mul_f32_e32 v102, v102, v103
	v_mul_f32_e32 v102, 0xbfb8aa3b, v102
	v_exp_f32_e32 v102, v102
	v_mul_f32_e32 v103, 0x3d372713, v97
	v_fma_f32 v103, v97, v103, 1.0
	v_add_f32_e32 v102, 1.0, v102
	v_rcp_f32_e32 v102, v102
	s_nop 0
	v_mul_f32_e32 v96, v96, v102
	v_mul_f32_e32 v102, 0x3fcc422a, v97
	v_mul_f32_e32 v102, v102, v103
	v_mul_f32_e32 v102, 0xbfb8aa3b, v102
	v_exp_f32_e32 v102, v102
	v_mul_f32_e32 v103, v93, v93
	v_fmac_f32_e32 v103, v92, v92
	v_add_f32_e32 v102, 1.0, v102
	v_rcp_f32_e32 v102, v102
	s_nop 0
	v_mul_f32_e32 v97, v97, v102
	v_mul_f32_e32 v102, v91, v91
	v_fmac_f32_e32 v102, v90, v90
	v_cvt_pk_bf16_f32 v90, v90, v91
	v_cvt_pk_bf16_f32 v91, v92, v93
	v_cvt_pk_bf16_f32 v92, v94, v95
	v_cvt_pk_bf16_f32 v93, v96, v97
	global_store_dwordx4 v[100:101], v[90:93], off nt
	v_add_f32_e32 v102, v102, v103
	v_mul_f32_e32 v103, v95, v95
	v_mul_f32_e32 v90, 0x3d372713, v82
	v_fma_f32 v90, v82, v90, 1.0
	v_mul_f32_e32 v0, v0, v90
	v_mul_f32_e32 v0, 0xbfb8aa3b, v0
	v_exp_f32_e32 v0, v0
	v_mul_f32_e32 v90, 0x3d372713, v83
	v_fma_f32 v90, v83, v90, 1.0
	v_mul_f32_e32 v104, v97, v97
	v_add_f32_e32 v0, 1.0, v0
	v_rcp_f32_e32 v0, v0
	v_fmac_f32_e32 v103, v94, v94
	v_fmac_f32_e32 v104, v96, v96
	v_add_f32_e32 v103, v103, v104
	v_mul_f32_e32 v0, v82, v0
	v_mul_f32_e32 v82, 0x3fcc422a, v83
	v_mul_f32_e32 v82, v82, v90
	v_mul_f32_e32 v82, 0xbfb8aa3b, v82
	v_exp_f32_e32 v82, v82
	v_mul_f32_e32 v90, 0x3d372713, v84
	v_fma_f32 v90, v84, v90, 1.0
	v_add_f32_e32 v102, v102, v103
	v_add_f32_e32 v82, 1.0, v82
	v_rcp_f32_e32 v82, v82
	s_nop 0
	v_mul_f32_e32 v82, v83, v82
	v_mul_f32_e32 v83, 0x3fcc422a, v84
	v_mul_f32_e32 v83, v83, v90
	v_mul_f32_e32 v83, 0xbfb8aa3b, v83
	v_exp_f32_e32 v83, v83
	v_mul_f32_e32 v90, 0x3d372713, v85
	v_fma_f32 v90, v85, v90, 1.0
	v_add_f32_e32 v83, 1.0, v83
	v_rcp_f32_e32 v83, v83
	s_nop 0
	v_mul_f32_e32 v83, v84, v83
	v_mul_f32_e32 v84, 0x3fcc422a, v85
	v_mul_f32_e32 v84, v84, v90
	v_mul_f32_e32 v84, 0xbfb8aa3b, v84
	v_exp_f32_e32 v84, v84
	v_mul_f32_e32 v90, 0x3d372713, v86
	v_fma_f32 v90, v86, v90, 1.0
	v_add_f32_e32 v84, 1.0, v84
	v_rcp_f32_e32 v84, v84
	s_nop 0
	v_mul_f32_e32 v84, v85, v84
	v_mul_f32_e32 v85, 0x3fcc422a, v86
	v_mul_f32_e32 v85, v85, v90
	v_mul_f32_e32 v85, 0xbfb8aa3b, v85
	v_exp_f32_e32 v85, v85
	v_mul_f32_e32 v90, 0x3d372713, v87
	v_fma_f32 v90, v87, v90, 1.0
	v_add_f32_e32 v85, 1.0, v85
	v_rcp_f32_e32 v85, v85
	s_nop 0
	v_mul_f32_e32 v85, v86, v85
	v_mul_f32_e32 v86, 0x3fcc422a, v87
	v_mul_f32_e32 v86, v86, v90
	v_mul_f32_e32 v86, 0xbfb8aa3b, v86
	v_exp_f32_e32 v86, v86
	v_mul_f32_e32 v90, 0x3d372713, v88
	v_fma_f32 v90, v88, v90, 1.0
	v_add_f32_e32 v86, 1.0, v86
	v_rcp_f32_e32 v86, v86
	s_nop 0
	v_mul_f32_e32 v86, v87, v86
	v_mul_f32_e32 v87, 0x3fcc422a, v88
	v_mul_f32_e32 v87, v87, v90
	v_mul_f32_e32 v87, 0xbfb8aa3b, v87
	v_exp_f32_e32 v87, v87
	v_mul_f32_e32 v90, 0x3d372713, v89
	v_fma_f32 v90, v89, v90, 1.0
	v_add_f32_e32 v87, 1.0, v87
	v_rcp_f32_e32 v87, v87
	s_nop 0
	v_mul_f32_e32 v87, v88, v87
	v_mul_f32_e32 v88, 0x3fcc422a, v89
	v_mul_f32_e32 v88, v88, v90
	v_mul_f32_e32 v88, 0xbfb8aa3b, v88
	v_exp_f32_e32 v88, v88
	v_mul_f32_e32 v90, v84, v84
	v_fmac_f32_e32 v90, v83, v83
	v_add_f32_e32 v88, 1.0, v88
	v_rcp_f32_e32 v88, v88
	s_nop 0
	v_mul_f32_e32 v88, v89, v88
	v_mul_f32_e32 v89, v82, v82
	v_fmac_f32_e32 v89, v0, v0
	v_add_f32_e32 v89, v89, v90
	v_mul_f32_e32 v90, v86, v86
	v_mul_f32_e32 v91, v88, v88
	v_fmac_f32_e32 v90, v85, v85
	v_fmac_f32_e32 v91, v87, v87
	v_add_f32_e32 v90, v90, v91
	v_add_f32_e32 v89, v89, v90
	v_add_f32_e32 v89, v102, v89
	v_cvt_pk_bf16_f32 v82, v0, v82
	v_mov_b32_e32 v0, v89
	s_nop 1
	v_permlane16_swap_b32_e32 v89, v0
	v_add_f32_e32 v0, v89, v0
	v_cvt_pk_bf16_f32 v83, v83, v84
	v_cvt_pk_bf16_f32 v84, v85, v86
	v_cvt_pk_bf16_f32 v85, v87, v88
	global_store_dwordx4 v[100:101], v[82:85], off offset:256 nt
	s_nop 1
	v_mov_b32_e32 v82, v0
	s_nop 1
	v_permlane32_swap_b32_e32 v0, v82
	s_and_saveexec_b64 s[0:1], s[2:3]
	s_cbranch_execz .LBB0_179
	v_add_f32_e32 v0, v0, v82
	v_lshlrev_b64 v[82:83], 7, v[98:99]
	s_lshl_b32 s36, s12, 2
	v_lshl_add_u64 v[82:83], v[138:139], 0, v[82:83]
	s_mov_b32 s37, s40
	v_lshl_add_u64 v[82:83], s[36:37], 2, v[82:83]
	s_lshl_b32 s36, s28, 2
	v_lshl_add_u64 v[82:83], v[82:83], 0, s[36:37]
	global_store_dword v[82:83], v0, off offset:-128
.LBB0_179:
	s_or_b64 exec, exec, s[0:1]
	v_add_f32_e32 v0, v171, v172
	v_fmamk_f32 v0, v0, 0x3a000000, v240
	v_rsq_f32_e32 v0, v0
	v_or_b32_e32 v82, 48, v150
	v_ashrrev_i32_e32 v83, 31, v82
	v_lshlrev_b64 v[84:85], 13, v[82:83]
	v_pk_mul_f32 v[74:75], v[74:75], v[0:1] op_sel_hi:[1,0]
	v_pk_mul_f32 v[76:77], v[76:77], v[0:1] op_sel_hi:[1,0]
	v_mul_f32_e32 v87, 0x3d372713, v74
	v_mul_f32_e32 v86, 0x3fcc422a, v74
	v_fma_f32 v87, v74, v87, 1.0
	v_mul_f32_e32 v86, v86, v87
	v_mul_f32_e32 v86, 0xbfb8aa3b, v86
	v_exp_f32_e32 v86, v86
	v_mul_f32_e32 v87, 0x3d372713, v75
	v_fma_f32 v87, v75, v87, 1.0
	v_pk_mul_f32 v[78:79], v[78:79], v[0:1] op_sel_hi:[1,0]
	v_add_f32_e32 v86, 1.0, v86
	v_rcp_f32_e32 v86, v86
	v_pk_mul_f32 v[80:81], v[80:81], v[0:1] op_sel_hi:[1,0]
	v_lshl_add_u64 v[84:85], v[152:153], 0, v[84:85]
	v_pk_mul_f32 v[66:67], v[66:67], v[0:1] op_sel_hi:[1,0]
	v_mul_f32_e32 v74, v74, v86
	v_mul_f32_e32 v86, 0x3fcc422a, v75
	v_mul_f32_e32 v86, v86, v87
	v_mul_f32_e32 v86, 0xbfb8aa3b, v86
	v_exp_f32_e32 v86, v86
	v_mul_f32_e32 v87, 0x3d372713, v76
	v_fma_f32 v87, v76, v87, 1.0
	v_pk_mul_f32 v[68:69], v[68:69], v[0:1] op_sel_hi:[1,0]
	v_add_f32_e32 v86, 1.0, v86
	v_rcp_f32_e32 v86, v86
	v_pk_mul_f32 v[72:73], v[72:73], v[0:1] op_sel_hi:[1,0]
	v_pk_mul_f32 v[70:71], v[70:71], v[0:1] op_sel_hi:[1,0]
	v_mul_f32_e32 v0, 0x3fcc422a, v66
	v_mul_f32_e32 v75, v75, v86
	v_mul_f32_e32 v86, 0x3fcc422a, v76
	v_mul_f32_e32 v86, v86, v87
	v_mul_f32_e32 v86, 0xbfb8aa3b, v86
	v_exp_f32_e32 v86, v86
	v_mul_f32_e32 v87, 0x3d372713, v77
	v_fma_f32 v87, v77, v87, 1.0
	v_add_f32_e32 v86, 1.0, v86
	v_rcp_f32_e32 v86, v86
	s_nop 0
	v_mul_f32_e32 v76, v76, v86
	v_mul_f32_e32 v86, 0x3fcc422a, v77
	v_mul_f32_e32 v86, v86, v87
	v_mul_f32_e32 v86, 0xbfb8aa3b, v86
	v_exp_f32_e32 v86, v86
	v_mul_f32_e32 v87, 0x3d372713, v78
	v_fma_f32 v87, v78, v87, 1.0
	v_add_f32_e32 v86, 1.0, v86
	v_rcp_f32_e32 v86, v86
	s_nop 0
	v_mul_f32_e32 v77, v77, v86
	v_mul_f32_e32 v86, 0x3fcc422a, v78
	v_mul_f32_e32 v86, v86, v87
	v_mul_f32_e32 v86, 0xbfb8aa3b, v86
	v_exp_f32_e32 v86, v86
	v_mul_f32_e32 v87, 0x3d372713, v79
	v_fma_f32 v87, v79, v87, 1.0
	v_add_f32_e32 v86, 1.0, v86
	v_rcp_f32_e32 v86, v86
	s_nop 0
	v_mul_f32_e32 v78, v78, v86
	v_mul_f32_e32 v86, 0x3fcc422a, v79
	v_mul_f32_e32 v86, v86, v87
	v_mul_f32_e32 v86, 0xbfb8aa3b, v86
	v_exp_f32_e32 v86, v86
	v_mul_f32_e32 v87, 0x3d372713, v80
	v_fma_f32 v87, v80, v87, 1.0
	v_add_f32_e32 v86, 1.0, v86
	v_rcp_f32_e32 v86, v86
	s_nop 0
	v_mul_f32_e32 v79, v79, v86
	v_mul_f32_e32 v86, 0x3fcc422a, v80
	v_mul_f32_e32 v86, v86, v87
	v_mul_f32_e32 v86, 0xbfb8aa3b, v86
	v_exp_f32_e32 v86, v86
	v_mul_f32_e32 v87, 0x3d372713, v81
	v_fma_f32 v87, v81, v87, 1.0
	v_add_f32_e32 v86, 1.0, v86
	v_rcp_f32_e32 v86, v86
	s_nop 0
	v_mul_f32_e32 v80, v80, v86
	v_mul_f32_e32 v86, 0x3fcc422a, v81
	v_mul_f32_e32 v86, v86, v87
	v_mul_f32_e32 v86, 0xbfb8aa3b, v86
	v_exp_f32_e32 v86, v86
	v_mul_f32_e32 v87, v77, v77
	v_fmac_f32_e32 v87, v76, v76
	v_add_f32_e32 v86, 1.0, v86
	v_rcp_f32_e32 v86, v86
	s_nop 0
	v_mul_f32_e32 v81, v81, v86
	v_mul_f32_e32 v86, v75, v75
	v_fmac_f32_e32 v86, v74, v74
	v_cvt_pk_bf16_f32 v74, v74, v75
	v_cvt_pk_bf16_f32 v75, v76, v77
	v_cvt_pk_bf16_f32 v76, v78, v79
	v_cvt_pk_bf16_f32 v77, v80, v81
	global_store_dwordx4 v[84:85], v[74:77], off nt
	v_add_f32_e32 v86, v86, v87
	v_mul_f32_e32 v87, v79, v79
	v_mul_f32_e32 v74, 0x3d372713, v66
	v_fma_f32 v74, v66, v74, 1.0
	v_mul_f32_e32 v0, v0, v74
	v_mul_f32_e32 v0, 0xbfb8aa3b, v0
	v_exp_f32_e32 v0, v0
	v_mul_f32_e32 v74, 0x3d372713, v67
	v_fma_f32 v74, v67, v74, 1.0
	v_mul_f32_e32 v88, v81, v81
	v_add_f32_e32 v0, 1.0, v0
	v_rcp_f32_e32 v0, v0
	v_fmac_f32_e32 v87, v78, v78
	v_fmac_f32_e32 v88, v80, v80
	v_add_f32_e32 v87, v87, v88
	v_mul_f32_e32 v0, v66, v0
	v_mul_f32_e32 v66, 0x3fcc422a, v67
	v_mul_f32_e32 v66, v66, v74
	v_mul_f32_e32 v66, 0xbfb8aa3b, v66
	v_exp_f32_e32 v66, v66
	v_mul_f32_e32 v74, 0x3d372713, v68
	v_fma_f32 v74, v68, v74, 1.0
	v_add_f32_e32 v86, v86, v87
	v_add_f32_e32 v66, 1.0, v66
	v_rcp_f32_e32 v66, v66
	s_nop 0
	v_mul_f32_e32 v66, v67, v66
	v_mul_f32_e32 v67, 0x3fcc422a, v68
	v_mul_f32_e32 v67, v67, v74
	v_mul_f32_e32 v67, 0xbfb8aa3b, v67
	v_exp_f32_e32 v67, v67
	v_mul_f32_e32 v74, 0x3d372713, v69
	v_fma_f32 v74, v69, v74, 1.0
	v_add_f32_e32 v67, 1.0, v67
	v_rcp_f32_e32 v67, v67
	s_nop 0
	v_mul_f32_e32 v67, v68, v67
	v_mul_f32_e32 v68, 0x3fcc422a, v69
	v_mul_f32_e32 v68, v68, v74
	v_mul_f32_e32 v68, 0xbfb8aa3b, v68
	v_exp_f32_e32 v68, v68
	v_mul_f32_e32 v74, 0x3d372713, v70
	v_fma_f32 v74, v70, v74, 1.0
	v_add_f32_e32 v68, 1.0, v68
	v_rcp_f32_e32 v68, v68
	s_nop 0
	v_mul_f32_e32 v68, v69, v68
	v_mul_f32_e32 v69, 0x3fcc422a, v70
	v_mul_f32_e32 v69, v69, v74
	v_mul_f32_e32 v69, 0xbfb8aa3b, v69
	v_exp_f32_e32 v69, v69
	v_mul_f32_e32 v74, 0x3d372713, v71
	v_fma_f32 v74, v71, v74, 1.0
	v_add_f32_e32 v69, 1.0, v69
	v_rcp_f32_e32 v69, v69
	s_nop 0
	v_mul_f32_e32 v69, v70, v69
	v_mul_f32_e32 v70, 0x3fcc422a, v71
	v_mul_f32_e32 v70, v70, v74
	v_mul_f32_e32 v70, 0xbfb8aa3b, v70
	v_exp_f32_e32 v70, v70
	v_mul_f32_e32 v74, 0x3d372713, v72
	v_fma_f32 v74, v72, v74, 1.0
	v_add_f32_e32 v70, 1.0, v70
	v_rcp_f32_e32 v70, v70
	s_nop 0
	v_mul_f32_e32 v70, v71, v70
	v_mul_f32_e32 v71, 0x3fcc422a, v72
	v_mul_f32_e32 v71, v71, v74
	v_mul_f32_e32 v71, 0xbfb8aa3b, v71
	v_exp_f32_e32 v71, v71
	v_mul_f32_e32 v74, 0x3d372713, v73
	v_fma_f32 v74, v73, v74, 1.0
	v_add_f32_e32 v71, 1.0, v71
	v_rcp_f32_e32 v71, v71
	s_nop 0
	v_mul_f32_e32 v71, v72, v71
	v_mul_f32_e32 v72, 0x3fcc422a, v73
	v_mul_f32_e32 v72, v72, v74
	v_mul_f32_e32 v72, 0xbfb8aa3b, v72
	v_exp_f32_e32 v72, v72
	v_mul_f32_e32 v74, v68, v68
	v_fmac_f32_e32 v74, v67, v67
	v_add_f32_e32 v72, 1.0, v72
	v_rcp_f32_e32 v72, v72
	s_nop 0
	v_mul_f32_e32 v72, v73, v72
	v_mul_f32_e32 v73, v66, v66
	v_fmac_f32_e32 v73, v0, v0
	v_add_f32_e32 v73, v73, v74
	v_mul_f32_e32 v74, v70, v70
	v_mul_f32_e32 v75, v72, v72
	v_fmac_f32_e32 v74, v69, v69
	v_fmac_f32_e32 v75, v71, v71
	v_add_f32_e32 v74, v74, v75
	v_add_f32_e32 v73, v73, v74
	v_add_f32_e32 v73, v86, v73
	v_cvt_pk_bf16_f32 v66, v0, v66
	v_mov_b32_e32 v0, v73
	s_nop 1
	v_permlane16_swap_b32_e32 v73, v0
	v_add_f32_e32 v0, v73, v0
	v_cvt_pk_bf16_f32 v67, v67, v68
	v_cvt_pk_bf16_f32 v68, v69, v70
	v_cvt_pk_bf16_f32 v69, v71, v72
	global_store_dwordx4 v[84:85], v[66:69], off offset:256 nt
	s_nop 1
	v_mov_b32_e32 v66, v0
	s_nop 1
	v_permlane32_swap_b32_e32 v0, v66
	s_and_saveexec_b64 s[0:1], s[2:3]
	s_cbranch_execz .LBB0_181
	v_add_f32_e32 v0, v0, v66
	v_lshlrev_b64 v[66:67], 7, v[82:83]
	s_lshl_b32 s36, s12, 2
	v_lshl_add_u64 v[66:67], v[138:139], 0, v[66:67]
	s_mov_b32 s37, s40
	v_lshl_add_u64 v[66:67], s[36:37], 2, v[66:67]
	s_lshl_b32 s36, s28, 2
	v_lshl_add_u64 v[66:67], v[66:67], 0, s[36:37]
	global_store_dword v[66:67], v0, off offset:-128
.LBB0_181:
	s_or_b64 exec, exec, s[0:1]
	v_add_f32_e32 v0, v169, v170
	v_fmamk_f32 v0, v0, 0x3a000000, v240
	v_rsq_f32_e32 v0, v0
	v_add_u32_e32 v66, 0x80, v150
	v_ashrrev_i32_e32 v67, 31, v66
	v_lshlrev_b64 v[68:69], 13, v[66:67]
	v_pk_mul_f32 v[58:59], v[58:59], v[0:1] op_sel_hi:[1,0]
	v_pk_mul_f32 v[60:61], v[60:61], v[0:1] op_sel_hi:[1,0]
	v_mul_f32_e32 v71, 0x3d372713, v58
	v_mul_f32_e32 v70, 0x3fcc422a, v58
	v_fma_f32 v71, v58, v71, 1.0
	v_mul_f32_e32 v70, v70, v71
	v_mul_f32_e32 v70, 0xbfb8aa3b, v70
	v_exp_f32_e32 v70, v70
	v_mul_f32_e32 v71, 0x3d372713, v59
	v_fma_f32 v71, v59, v71, 1.0
	v_pk_mul_f32 v[62:63], v[62:63], v[0:1] op_sel_hi:[1,0]
	v_add_f32_e32 v70, 1.0, v70
	v_rcp_f32_e32 v70, v70
	v_pk_mul_f32 v[64:65], v[64:65], v[0:1] op_sel_hi:[1,0]
	v_lshl_add_u64 v[68:69], v[152:153], 0, v[68:69]
	v_pk_mul_f32 v[50:51], v[50:51], v[0:1] op_sel_hi:[1,0]
	v_mul_f32_e32 v58, v58, v70
	v_mul_f32_e32 v70, 0x3fcc422a, v59
	v_mul_f32_e32 v70, v70, v71
	v_mul_f32_e32 v70, 0xbfb8aa3b, v70
	v_exp_f32_e32 v70, v70
	v_mul_f32_e32 v71, 0x3d372713, v60
	v_fma_f32 v71, v60, v71, 1.0
	v_pk_mul_f32 v[52:53], v[52:53], v[0:1] op_sel_hi:[1,0]
	v_add_f32_e32 v70, 1.0, v70
	v_rcp_f32_e32 v70, v70
	v_pk_mul_f32 v[56:57], v[56:57], v[0:1] op_sel_hi:[1,0]
	v_pk_mul_f32 v[54:55], v[54:55], v[0:1] op_sel_hi:[1,0]
	v_mul_f32_e32 v0, 0x3fcc422a, v50
	v_mul_f32_e32 v59, v59, v70
	v_mul_f32_e32 v70, 0x3fcc422a, v60
	v_mul_f32_e32 v70, v70, v71
	v_mul_f32_e32 v70, 0xbfb8aa3b, v70
	v_exp_f32_e32 v70, v70
	v_mul_f32_e32 v71, 0x3d372713, v61
	v_fma_f32 v71, v61, v71, 1.0
	v_add_f32_e32 v70, 1.0, v70
	v_rcp_f32_e32 v70, v70
	s_nop 0
	v_mul_f32_e32 v60, v60, v70
	v_mul_f32_e32 v70, 0x3fcc422a, v61
	v_mul_f32_e32 v70, v70, v71
	v_mul_f32_e32 v70, 0xbfb8aa3b, v70
	v_exp_f32_e32 v70, v70
	v_mul_f32_e32 v71, 0x3d372713, v62
	v_fma_f32 v71, v62, v71, 1.0
	v_add_f32_e32 v70, 1.0, v70
	v_rcp_f32_e32 v70, v70
	s_nop 0
	v_mul_f32_e32 v61, v61, v70
	v_mul_f32_e32 v70, 0x3fcc422a, v62
	v_mul_f32_e32 v70, v70, v71
	v_mul_f32_e32 v70, 0xbfb8aa3b, v70
	v_exp_f32_e32 v70, v70
	v_mul_f32_e32 v71, 0x3d372713, v63
	v_fma_f32 v71, v63, v71, 1.0
	v_add_f32_e32 v70, 1.0, v70
	v_rcp_f32_e32 v70, v70
	s_nop 0
	v_mul_f32_e32 v62, v62, v70
	v_mul_f32_e32 v70, 0x3fcc422a, v63
	v_mul_f32_e32 v70, v70, v71
	v_mul_f32_e32 v70, 0xbfb8aa3b, v70
	v_exp_f32_e32 v70, v70
	v_mul_f32_e32 v71, 0x3d372713, v64
	v_fma_f32 v71, v64, v71, 1.0
	v_add_f32_e32 v70, 1.0, v70
	v_rcp_f32_e32 v70, v70
	s_nop 0
	v_mul_f32_e32 v63, v63, v70
	v_mul_f32_e32 v70, 0x3fcc422a, v64
	v_mul_f32_e32 v70, v70, v71
	v_mul_f32_e32 v70, 0xbfb8aa3b, v70
	v_exp_f32_e32 v70, v70
	v_mul_f32_e32 v71, 0x3d372713, v65
	v_fma_f32 v71, v65, v71, 1.0
	v_add_f32_e32 v70, 1.0, v70
	v_rcp_f32_e32 v70, v70
	s_nop 0
	v_mul_f32_e32 v64, v64, v70
	v_mul_f32_e32 v70, 0x3fcc422a, v65
	v_mul_f32_e32 v70, v70, v71
	v_mul_f32_e32 v70, 0xbfb8aa3b, v70
	v_exp_f32_e32 v70, v70
	v_mul_f32_e32 v71, v61, v61
	v_fmac_f32_e32 v71, v60, v60
	v_add_f32_e32 v70, 1.0, v70
	v_rcp_f32_e32 v70, v70
	s_nop 0
	v_mul_f32_e32 v65, v65, v70
	v_mul_f32_e32 v70, v59, v59
	v_fmac_f32_e32 v70, v58, v58
	v_cvt_pk_bf16_f32 v58, v58, v59
	v_cvt_pk_bf16_f32 v59, v60, v61
	v_cvt_pk_bf16_f32 v60, v62, v63
	v_cvt_pk_bf16_f32 v61, v64, v65
	global_store_dwordx4 v[68:69], v[58:61], off nt
	v_add_f32_e32 v70, v70, v71
	v_mul_f32_e32 v71, v63, v63
	v_mul_f32_e32 v58, 0x3d372713, v50
	v_fma_f32 v58, v50, v58, 1.0
	v_mul_f32_e32 v0, v0, v58
	v_mul_f32_e32 v0, 0xbfb8aa3b, v0
	v_exp_f32_e32 v0, v0
	v_mul_f32_e32 v58, 0x3d372713, v51
	v_fma_f32 v58, v51, v58, 1.0
	v_mul_f32_e32 v72, v65, v65
	v_add_f32_e32 v0, 1.0, v0
	v_rcp_f32_e32 v0, v0
	v_fmac_f32_e32 v71, v62, v62
	v_fmac_f32_e32 v72, v64, v64
	v_add_f32_e32 v71, v71, v72
	v_mul_f32_e32 v0, v50, v0
	v_mul_f32_e32 v50, 0x3fcc422a, v51
	v_mul_f32_e32 v50, v50, v58
	v_mul_f32_e32 v50, 0xbfb8aa3b, v50
	v_exp_f32_e32 v50, v50
	v_mul_f32_e32 v58, 0x3d372713, v52
	v_fma_f32 v58, v52, v58, 1.0
	v_add_f32_e32 v70, v70, v71
	v_add_f32_e32 v50, 1.0, v50
	v_rcp_f32_e32 v50, v50
	s_nop 0
	v_mul_f32_e32 v50, v51, v50
	v_mul_f32_e32 v51, 0x3fcc422a, v52
	v_mul_f32_e32 v51, v51, v58
	v_mul_f32_e32 v51, 0xbfb8aa3b, v51
	v_exp_f32_e32 v51, v51
	v_mul_f32_e32 v58, 0x3d372713, v53
	v_fma_f32 v58, v53, v58, 1.0
	v_add_f32_e32 v51, 1.0, v51
	v_rcp_f32_e32 v51, v51
	s_nop 0
	v_mul_f32_e32 v51, v52, v51
	v_mul_f32_e32 v52, 0x3fcc422a, v53
	v_mul_f32_e32 v52, v52, v58
	v_mul_f32_e32 v52, 0xbfb8aa3b, v52
	v_exp_f32_e32 v52, v52
	v_mul_f32_e32 v58, 0x3d372713, v54
	v_fma_f32 v58, v54, v58, 1.0
	v_add_f32_e32 v52, 1.0, v52
	v_rcp_f32_e32 v52, v52
	s_nop 0
	v_mul_f32_e32 v52, v53, v52
	v_mul_f32_e32 v53, 0x3fcc422a, v54
	v_mul_f32_e32 v53, v53, v58
	v_mul_f32_e32 v53, 0xbfb8aa3b, v53
	v_exp_f32_e32 v53, v53
	v_mul_f32_e32 v58, 0x3d372713, v55
	v_fma_f32 v58, v55, v58, 1.0
	v_add_f32_e32 v53, 1.0, v53
	v_rcp_f32_e32 v53, v53
	s_nop 0
	v_mul_f32_e32 v53, v54, v53
	v_mul_f32_e32 v54, 0x3fcc422a, v55
	v_mul_f32_e32 v54, v54, v58
	v_mul_f32_e32 v54, 0xbfb8aa3b, v54
	v_exp_f32_e32 v54, v54
	v_mul_f32_e32 v58, 0x3d372713, v56
	v_fma_f32 v58, v56, v58, 1.0
	v_add_f32_e32 v54, 1.0, v54
	v_rcp_f32_e32 v54, v54
	s_nop 0
	v_mul_f32_e32 v54, v55, v54
	v_mul_f32_e32 v55, 0x3fcc422a, v56
	v_mul_f32_e32 v55, v55, v58
	v_mul_f32_e32 v55, 0xbfb8aa3b, v55
	v_exp_f32_e32 v55, v55
	v_mul_f32_e32 v58, 0x3d372713, v57
	v_fma_f32 v58, v57, v58, 1.0
	v_add_f32_e32 v55, 1.0, v55
	v_rcp_f32_e32 v55, v55
	s_nop 0
	v_mul_f32_e32 v55, v56, v55
	v_mul_f32_e32 v56, 0x3fcc422a, v57
	v_mul_f32_e32 v56, v56, v58
	v_mul_f32_e32 v56, 0xbfb8aa3b, v56
	v_exp_f32_e32 v56, v56
	v_mul_f32_e32 v58, v52, v52
	v_fmac_f32_e32 v58, v51, v51
	v_add_f32_e32 v56, 1.0, v56
	v_rcp_f32_e32 v56, v56
	s_nop 0
	v_mul_f32_e32 v56, v57, v56
	v_mul_f32_e32 v57, v50, v50
	v_fmac_f32_e32 v57, v0, v0
	v_add_f32_e32 v57, v57, v58
	v_mul_f32_e32 v58, v54, v54
	v_mul_f32_e32 v59, v56, v56
	v_fmac_f32_e32 v58, v53, v53
	v_fmac_f32_e32 v59, v55, v55
	v_add_f32_e32 v58, v58, v59
	v_add_f32_e32 v57, v57, v58
	v_add_f32_e32 v57, v70, v57
	v_cvt_pk_bf16_f32 v50, v0, v50
	v_mov_b32_e32 v0, v57
	s_nop 1
	v_permlane16_swap_b32_e32 v57, v0
	v_add_f32_e32 v0, v57, v0
	v_cvt_pk_bf16_f32 v51, v51, v52
	v_cvt_pk_bf16_f32 v52, v53, v54
	v_cvt_pk_bf16_f32 v53, v55, v56
	global_store_dwordx4 v[68:69], v[50:53], off offset:256 nt
	s_nop 1
	v_mov_b32_e32 v50, v0
	s_nop 1
	v_permlane32_swap_b32_e32 v0, v50
	s_and_saveexec_b64 s[0:1], s[2:3]
	s_cbranch_execz .LBB0_183
	v_add_f32_e32 v0, v0, v50
	v_lshlrev_b64 v[50:51], 7, v[66:67]
	s_lshl_b32 s36, s12, 2
	v_lshl_add_u64 v[50:51], v[138:139], 0, v[50:51]
	s_mov_b32 s37, s40
	v_lshl_add_u64 v[50:51], s[36:37], 2, v[50:51]
	s_lshl_b32 s36, s28, 2
	v_lshl_add_u64 v[50:51], v[50:51], 0, s[36:37]
	global_store_dword v[50:51], v0, off offset:-128
.LBB0_183:
	s_or_b64 exec, exec, s[0:1]
	v_add_f32_e32 v0, v161, v168
	v_fmamk_f32 v0, v0, 0x3a000000, v240
	v_rsq_f32_e32 v0, v0
	v_add_u32_e32 v50, 0x90, v150
	v_ashrrev_i32_e32 v51, 31, v50
	v_lshlrev_b64 v[52:53], 13, v[50:51]
	v_pk_mul_f32 v[42:43], v[42:43], v[0:1] op_sel_hi:[1,0]
	v_pk_mul_f32 v[44:45], v[44:45], v[0:1] op_sel_hi:[1,0]
	v_mul_f32_e32 v55, 0x3d372713, v42
	v_mul_f32_e32 v54, 0x3fcc422a, v42
	v_fma_f32 v55, v42, v55, 1.0
	v_mul_f32_e32 v54, v54, v55
	v_mul_f32_e32 v54, 0xbfb8aa3b, v54
	v_exp_f32_e32 v54, v54
	v_mul_f32_e32 v55, 0x3d372713, v43
	v_fma_f32 v55, v43, v55, 1.0
	v_pk_mul_f32 v[46:47], v[46:47], v[0:1] op_sel_hi:[1,0]
	v_add_f32_e32 v54, 1.0, v54
	v_rcp_f32_e32 v54, v54
	v_pk_mul_f32 v[48:49], v[48:49], v[0:1] op_sel_hi:[1,0]
	v_lshl_add_u64 v[52:53], v[152:153], 0, v[52:53]
	v_pk_mul_f32 v[34:35], v[34:35], v[0:1] op_sel_hi:[1,0]
	v_mul_f32_e32 v42, v42, v54
	v_mul_f32_e32 v54, 0x3fcc422a, v43
	v_mul_f32_e32 v54, v54, v55
	v_mul_f32_e32 v54, 0xbfb8aa3b, v54
	v_exp_f32_e32 v54, v54
	v_mul_f32_e32 v55, 0x3d372713, v44
	v_fma_f32 v55, v44, v55, 1.0
	v_pk_mul_f32 v[36:37], v[36:37], v[0:1] op_sel_hi:[1,0]
	v_add_f32_e32 v54, 1.0, v54
	v_rcp_f32_e32 v54, v54
	v_pk_mul_f32 v[40:41], v[40:41], v[0:1] op_sel_hi:[1,0]
	v_pk_mul_f32 v[38:39], v[38:39], v[0:1] op_sel_hi:[1,0]
	v_mul_f32_e32 v0, 0x3fcc422a, v34
	v_mul_f32_e32 v43, v43, v54
	v_mul_f32_e32 v54, 0x3fcc422a, v44
	v_mul_f32_e32 v54, v54, v55
	v_mul_f32_e32 v54, 0xbfb8aa3b, v54
	v_exp_f32_e32 v54, v54
	v_mul_f32_e32 v55, 0x3d372713, v45
	v_fma_f32 v55, v45, v55, 1.0
	v_add_f32_e32 v54, 1.0, v54
	v_rcp_f32_e32 v54, v54
	s_nop 0
	v_mul_f32_e32 v44, v44, v54
	v_mul_f32_e32 v54, 0x3fcc422a, v45
	v_mul_f32_e32 v54, v54, v55
	v_mul_f32_e32 v54, 0xbfb8aa3b, v54
	v_exp_f32_e32 v54, v54
	v_mul_f32_e32 v55, 0x3d372713, v46
	v_fma_f32 v55, v46, v55, 1.0
	v_add_f32_e32 v54, 1.0, v54
	v_rcp_f32_e32 v54, v54
	s_nop 0
	v_mul_f32_e32 v45, v45, v54
	v_mul_f32_e32 v54, 0x3fcc422a, v46
	v_mul_f32_e32 v54, v54, v55
	v_mul_f32_e32 v54, 0xbfb8aa3b, v54
	v_exp_f32_e32 v54, v54
	v_mul_f32_e32 v55, 0x3d372713, v47
	v_fma_f32 v55, v47, v55, 1.0
	v_add_f32_e32 v54, 1.0, v54
	v_rcp_f32_e32 v54, v54
	s_nop 0
	v_mul_f32_e32 v46, v46, v54
	v_mul_f32_e32 v54, 0x3fcc422a, v47
	v_mul_f32_e32 v54, v54, v55
	v_mul_f32_e32 v54, 0xbfb8aa3b, v54
	v_exp_f32_e32 v54, v54
	v_mul_f32_e32 v55, 0x3d372713, v48
	v_fma_f32 v55, v48, v55, 1.0
	v_add_f32_e32 v54, 1.0, v54
	v_rcp_f32_e32 v54, v54
	s_nop 0
	v_mul_f32_e32 v47, v47, v54
	v_mul_f32_e32 v54, 0x3fcc422a, v48
	v_mul_f32_e32 v54, v54, v55
	v_mul_f32_e32 v54, 0xbfb8aa3b, v54
	v_exp_f32_e32 v54, v54
	v_mul_f32_e32 v55, 0x3d372713, v49
	v_fma_f32 v55, v49, v55, 1.0
	v_add_f32_e32 v54, 1.0, v54
	v_rcp_f32_e32 v54, v54
	s_nop 0
	v_mul_f32_e32 v48, v48, v54
	v_mul_f32_e32 v54, 0x3fcc422a, v49
	v_mul_f32_e32 v54, v54, v55
	v_mul_f32_e32 v54, 0xbfb8aa3b, v54
	v_exp_f32_e32 v54, v54
	v_mul_f32_e32 v55, v45, v45
	v_fmac_f32_e32 v55, v44, v44
	v_add_f32_e32 v54, 1.0, v54
	v_rcp_f32_e32 v54, v54
	s_nop 0
	v_mul_f32_e32 v49, v49, v54
	v_mul_f32_e32 v54, v43, v43
	v_fmac_f32_e32 v54, v42, v42
	v_cvt_pk_bf16_f32 v42, v42, v43
	v_cvt_pk_bf16_f32 v43, v44, v45
	v_cvt_pk_bf16_f32 v44, v46, v47
	v_cvt_pk_bf16_f32 v45, v48, v49
	global_store_dwordx4 v[52:53], v[42:45], off nt
	v_add_f32_e32 v54, v54, v55
	v_mul_f32_e32 v55, v47, v47
	v_mul_f32_e32 v42, 0x3d372713, v34
	v_fma_f32 v42, v34, v42, 1.0
	v_mul_f32_e32 v0, v0, v42
	v_mul_f32_e32 v0, 0xbfb8aa3b, v0
	v_exp_f32_e32 v0, v0
	v_mul_f32_e32 v42, 0x3d372713, v35
	v_fma_f32 v42, v35, v42, 1.0
	v_mul_f32_e32 v56, v49, v49
	v_add_f32_e32 v0, 1.0, v0
	v_rcp_f32_e32 v0, v0
	v_fmac_f32_e32 v55, v46, v46
	v_fmac_f32_e32 v56, v48, v48
	v_add_f32_e32 v55, v55, v56
	v_mul_f32_e32 v0, v34, v0
	v_mul_f32_e32 v34, 0x3fcc422a, v35
	v_mul_f32_e32 v34, v34, v42
	v_mul_f32_e32 v34, 0xbfb8aa3b, v34
	v_exp_f32_e32 v34, v34
	v_mul_f32_e32 v42, 0x3d372713, v36
	v_fma_f32 v42, v36, v42, 1.0
	v_add_f32_e32 v54, v54, v55
	v_add_f32_e32 v34, 1.0, v34
	v_rcp_f32_e32 v34, v34
	s_nop 0
	v_mul_f32_e32 v34, v35, v34
	v_mul_f32_e32 v35, 0x3fcc422a, v36
	v_mul_f32_e32 v35, v35, v42
	v_mul_f32_e32 v35, 0xbfb8aa3b, v35
	v_exp_f32_e32 v35, v35
	v_mul_f32_e32 v42, 0x3d372713, v37
	v_fma_f32 v42, v37, v42, 1.0
	v_add_f32_e32 v35, 1.0, v35
	v_rcp_f32_e32 v35, v35
	s_nop 0
	v_mul_f32_e32 v35, v36, v35
	v_mul_f32_e32 v36, 0x3fcc422a, v37
	v_mul_f32_e32 v36, v36, v42
	v_mul_f32_e32 v36, 0xbfb8aa3b, v36
	v_exp_f32_e32 v36, v36
	v_mul_f32_e32 v42, 0x3d372713, v38
	v_fma_f32 v42, v38, v42, 1.0
	v_add_f32_e32 v36, 1.0, v36
	v_rcp_f32_e32 v36, v36
	s_nop 0
	v_mul_f32_e32 v36, v37, v36
	v_mul_f32_e32 v37, 0x3fcc422a, v38
	v_mul_f32_e32 v37, v37, v42
	v_mul_f32_e32 v37, 0xbfb8aa3b, v37
	v_exp_f32_e32 v37, v37
	v_mul_f32_e32 v42, 0x3d372713, v39
	v_fma_f32 v42, v39, v42, 1.0
	v_add_f32_e32 v37, 1.0, v37
	v_rcp_f32_e32 v37, v37
	s_nop 0
	v_mul_f32_e32 v37, v38, v37
	v_mul_f32_e32 v38, 0x3fcc422a, v39
	v_mul_f32_e32 v38, v38, v42
	v_mul_f32_e32 v38, 0xbfb8aa3b, v38
	v_exp_f32_e32 v38, v38
	v_mul_f32_e32 v42, 0x3d372713, v40
	v_fma_f32 v42, v40, v42, 1.0
	v_add_f32_e32 v38, 1.0, v38
	v_rcp_f32_e32 v38, v38
	s_nop 0
	v_mul_f32_e32 v38, v39, v38
	v_mul_f32_e32 v39, 0x3fcc422a, v40
	v_mul_f32_e32 v39, v39, v42
	v_mul_f32_e32 v39, 0xbfb8aa3b, v39
	v_exp_f32_e32 v39, v39
	v_mul_f32_e32 v42, 0x3d372713, v41
	v_fma_f32 v42, v41, v42, 1.0
	v_add_f32_e32 v39, 1.0, v39
	v_rcp_f32_e32 v39, v39
	s_nop 0
	v_mul_f32_e32 v39, v40, v39
	v_mul_f32_e32 v40, 0x3fcc422a, v41
	v_mul_f32_e32 v40, v40, v42
	v_mul_f32_e32 v40, 0xbfb8aa3b, v40
	v_exp_f32_e32 v40, v40
	v_mul_f32_e32 v42, v36, v36
	v_fmac_f32_e32 v42, v35, v35
	v_add_f32_e32 v40, 1.0, v40
	v_rcp_f32_e32 v40, v40
	s_nop 0
	v_mul_f32_e32 v40, v41, v40
	v_mul_f32_e32 v41, v34, v34
	v_fmac_f32_e32 v41, v0, v0
	v_add_f32_e32 v41, v41, v42
	v_mul_f32_e32 v42, v38, v38
	v_mul_f32_e32 v43, v40, v40
	v_fmac_f32_e32 v42, v37, v37
	v_fmac_f32_e32 v43, v39, v39
	v_add_f32_e32 v42, v42, v43
	v_add_f32_e32 v41, v41, v42
	v_add_f32_e32 v41, v54, v41
	v_cvt_pk_bf16_f32 v34, v0, v34
	v_mov_b32_e32 v0, v41
	s_nop 1
	v_permlane16_swap_b32_e32 v41, v0
	v_add_f32_e32 v0, v41, v0
	v_cvt_pk_bf16_f32 v35, v35, v36
	v_cvt_pk_bf16_f32 v36, v37, v38
	v_cvt_pk_bf16_f32 v37, v39, v40
	global_store_dwordx4 v[52:53], v[34:37], off offset:256 nt
	s_nop 1
	v_mov_b32_e32 v34, v0
	s_nop 1
	v_permlane32_swap_b32_e32 v0, v34
	s_and_saveexec_b64 s[0:1], s[2:3]
	s_cbranch_execz .LBB0_185
	v_add_f32_e32 v0, v0, v34
	v_lshlrev_b64 v[34:35], 7, v[50:51]
	s_lshl_b32 s36, s12, 2
	v_lshl_add_u64 v[34:35], v[138:139], 0, v[34:35]
	s_mov_b32 s37, s40
	v_lshl_add_u64 v[34:35], s[36:37], 2, v[34:35]
	s_lshl_b32 s36, s28, 2
	v_lshl_add_u64 v[34:35], v[34:35], 0, s[36:37]
	global_store_dword v[34:35], v0, off offset:-128
.LBB0_185:
	s_or_b64 exec, exec, s[0:1]
	v_add_f32_e32 v0, v159, v160
	v_fmamk_f32 v0, v0, 0x3a000000, v240
	v_rsq_f32_e32 v0, v0
	v_add_u32_e32 v34, 0xa0, v150
	v_ashrrev_i32_e32 v35, 31, v34
	v_lshlrev_b64 v[36:37], 13, v[34:35]
	v_pk_mul_f32 v[26:27], v[26:27], v[0:1] op_sel_hi:[1,0]
	v_pk_mul_f32 v[28:29], v[28:29], v[0:1] op_sel_hi:[1,0]
	v_mul_f32_e32 v39, 0x3d372713, v26
	v_mul_f32_e32 v38, 0x3fcc422a, v26
	v_fma_f32 v39, v26, v39, 1.0
	v_mul_f32_e32 v38, v38, v39
	v_mul_f32_e32 v38, 0xbfb8aa3b, v38
	v_exp_f32_e32 v38, v38
	v_mul_f32_e32 v39, 0x3d372713, v27
	v_fma_f32 v39, v27, v39, 1.0
	v_pk_mul_f32 v[30:31], v[30:31], v[0:1] op_sel_hi:[1,0]
	v_add_f32_e32 v38, 1.0, v38
	v_rcp_f32_e32 v38, v38
	v_pk_mul_f32 v[32:33], v[32:33], v[0:1] op_sel_hi:[1,0]
	v_lshl_add_u64 v[36:37], v[152:153], 0, v[36:37]
	v_pk_mul_f32 v[18:19], v[18:19], v[0:1] op_sel_hi:[1,0]
	v_mul_f32_e32 v26, v26, v38
	v_mul_f32_e32 v38, 0x3fcc422a, v27
	v_mul_f32_e32 v38, v38, v39
	v_mul_f32_e32 v38, 0xbfb8aa3b, v38
	v_exp_f32_e32 v38, v38
	v_mul_f32_e32 v39, 0x3d372713, v28
	v_fma_f32 v39, v28, v39, 1.0
	v_pk_mul_f32 v[20:21], v[20:21], v[0:1] op_sel_hi:[1,0]
	v_add_f32_e32 v38, 1.0, v38
	v_rcp_f32_e32 v38, v38
	v_pk_mul_f32 v[24:25], v[24:25], v[0:1] op_sel_hi:[1,0]
	v_pk_mul_f32 v[22:23], v[22:23], v[0:1] op_sel_hi:[1,0]
	v_mul_f32_e32 v0, 0x3fcc422a, v18
	v_mul_f32_e32 v27, v27, v38
	v_mul_f32_e32 v38, 0x3fcc422a, v28
	v_mul_f32_e32 v38, v38, v39
	v_mul_f32_e32 v38, 0xbfb8aa3b, v38
	v_exp_f32_e32 v38, v38
	v_mul_f32_e32 v39, 0x3d372713, v29
	v_fma_f32 v39, v29, v39, 1.0
	v_add_f32_e32 v38, 1.0, v38
	v_rcp_f32_e32 v38, v38
	s_nop 0
	v_mul_f32_e32 v28, v28, v38
	v_mul_f32_e32 v38, 0x3fcc422a, v29
	v_mul_f32_e32 v38, v38, v39
	v_mul_f32_e32 v38, 0xbfb8aa3b, v38
	v_exp_f32_e32 v38, v38
	v_mul_f32_e32 v39, 0x3d372713, v30
	v_fma_f32 v39, v30, v39, 1.0
	v_add_f32_e32 v38, 1.0, v38
	v_rcp_f32_e32 v38, v38
	s_nop 0
	v_mul_f32_e32 v29, v29, v38
	v_mul_f32_e32 v38, 0x3fcc422a, v30
	v_mul_f32_e32 v38, v38, v39
	v_mul_f32_e32 v38, 0xbfb8aa3b, v38
	v_exp_f32_e32 v38, v38
	v_mul_f32_e32 v39, 0x3d372713, v31
	v_fma_f32 v39, v31, v39, 1.0
	v_add_f32_e32 v38, 1.0, v38
	v_rcp_f32_e32 v38, v38
	s_nop 0
	v_mul_f32_e32 v30, v30, v38
	v_mul_f32_e32 v38, 0x3fcc422a, v31
	v_mul_f32_e32 v38, v38, v39
	v_mul_f32_e32 v38, 0xbfb8aa3b, v38
	v_exp_f32_e32 v38, v38
	v_mul_f32_e32 v39, 0x3d372713, v32
	v_fma_f32 v39, v32, v39, 1.0
	v_add_f32_e32 v38, 1.0, v38
	v_rcp_f32_e32 v38, v38
	s_nop 0
	v_mul_f32_e32 v31, v31, v38
	v_mul_f32_e32 v38, 0x3fcc422a, v32
	v_mul_f32_e32 v38, v38, v39
	v_mul_f32_e32 v38, 0xbfb8aa3b, v38
	v_exp_f32_e32 v38, v38
	v_mul_f32_e32 v39, 0x3d372713, v33
	v_fma_f32 v39, v33, v39, 1.0
	v_add_f32_e32 v38, 1.0, v38
	v_rcp_f32_e32 v38, v38
	s_nop 0
	v_mul_f32_e32 v32, v32, v38
	v_mul_f32_e32 v38, 0x3fcc422a, v33
	v_mul_f32_e32 v38, v38, v39
	v_mul_f32_e32 v38, 0xbfb8aa3b, v38
	v_exp_f32_e32 v38, v38
	v_mul_f32_e32 v39, v29, v29
	v_fmac_f32_e32 v39, v28, v28
	v_add_f32_e32 v38, 1.0, v38
	v_rcp_f32_e32 v38, v38
	s_nop 0
	v_mul_f32_e32 v33, v33, v38
	v_mul_f32_e32 v38, v27, v27
	v_fmac_f32_e32 v38, v26, v26
	v_cvt_pk_bf16_f32 v26, v26, v27
	v_cvt_pk_bf16_f32 v27, v28, v29
	v_cvt_pk_bf16_f32 v28, v30, v31
	v_cvt_pk_bf16_f32 v29, v32, v33
	global_store_dwordx4 v[36:37], v[26:29], off nt
	v_add_f32_e32 v38, v38, v39
	v_mul_f32_e32 v39, v31, v31
	v_mul_f32_e32 v26, 0x3d372713, v18
	v_fma_f32 v26, v18, v26, 1.0
	v_mul_f32_e32 v0, v0, v26
	v_mul_f32_e32 v0, 0xbfb8aa3b, v0
	v_exp_f32_e32 v0, v0
	v_mul_f32_e32 v26, 0x3d372713, v19
	v_fma_f32 v26, v19, v26, 1.0
	v_mul_f32_e32 v40, v33, v33
	v_add_f32_e32 v0, 1.0, v0
	v_rcp_f32_e32 v0, v0
	v_fmac_f32_e32 v39, v30, v30
	v_fmac_f32_e32 v40, v32, v32
	v_add_f32_e32 v39, v39, v40
	v_mul_f32_e32 v0, v18, v0
	v_mul_f32_e32 v18, 0x3fcc422a, v19
	v_mul_f32_e32 v18, v18, v26
	v_mul_f32_e32 v18, 0xbfb8aa3b, v18
	v_exp_f32_e32 v18, v18
	v_mul_f32_e32 v26, 0x3d372713, v20
	v_fma_f32 v26, v20, v26, 1.0
	v_add_f32_e32 v38, v38, v39
	v_add_f32_e32 v18, 1.0, v18
	v_rcp_f32_e32 v18, v18
	s_nop 0
	v_mul_f32_e32 v18, v19, v18
	v_mul_f32_e32 v19, 0x3fcc422a, v20
	v_mul_f32_e32 v19, v19, v26
	v_mul_f32_e32 v19, 0xbfb8aa3b, v19
	v_exp_f32_e32 v19, v19
	v_mul_f32_e32 v26, 0x3d372713, v21
	v_fma_f32 v26, v21, v26, 1.0
	v_add_f32_e32 v19, 1.0, v19
	v_rcp_f32_e32 v19, v19
	s_nop 0
	v_mul_f32_e32 v19, v20, v19
	v_mul_f32_e32 v20, 0x3fcc422a, v21
	v_mul_f32_e32 v20, v20, v26
	v_mul_f32_e32 v20, 0xbfb8aa3b, v20
	v_exp_f32_e32 v20, v20
	v_mul_f32_e32 v26, 0x3d372713, v22
	v_fma_f32 v26, v22, v26, 1.0
	v_add_f32_e32 v20, 1.0, v20
	v_rcp_f32_e32 v20, v20
	s_nop 0
	v_mul_f32_e32 v20, v21, v20
	v_mul_f32_e32 v21, 0x3fcc422a, v22
	v_mul_f32_e32 v21, v21, v26
	v_mul_f32_e32 v21, 0xbfb8aa3b, v21
	v_exp_f32_e32 v21, v21
	v_mul_f32_e32 v26, 0x3d372713, v23
	v_fma_f32 v26, v23, v26, 1.0
	v_add_f32_e32 v21, 1.0, v21
	v_rcp_f32_e32 v21, v21
	s_nop 0
	v_mul_f32_e32 v21, v22, v21
	v_mul_f32_e32 v22, 0x3fcc422a, v23
	v_mul_f32_e32 v22, v22, v26
	v_mul_f32_e32 v22, 0xbfb8aa3b, v22
	v_exp_f32_e32 v22, v22
	v_mul_f32_e32 v26, 0x3d372713, v24
	v_fma_f32 v26, v24, v26, 1.0
	v_add_f32_e32 v22, 1.0, v22
	v_rcp_f32_e32 v22, v22
	s_nop 0
	v_mul_f32_e32 v22, v23, v22
	v_mul_f32_e32 v23, 0x3fcc422a, v24
	v_mul_f32_e32 v23, v23, v26
	v_mul_f32_e32 v23, 0xbfb8aa3b, v23
	v_exp_f32_e32 v23, v23
	v_mul_f32_e32 v26, 0x3d372713, v25
	v_fma_f32 v26, v25, v26, 1.0
	v_add_f32_e32 v23, 1.0, v23
	v_rcp_f32_e32 v23, v23
	s_nop 0
	v_mul_f32_e32 v23, v24, v23
	v_mul_f32_e32 v24, 0x3fcc422a, v25
	v_mul_f32_e32 v24, v24, v26
	v_mul_f32_e32 v24, 0xbfb8aa3b, v24
	v_exp_f32_e32 v24, v24
	v_mul_f32_e32 v26, v20, v20
	v_fmac_f32_e32 v26, v19, v19
	v_add_f32_e32 v24, 1.0, v24
	v_rcp_f32_e32 v24, v24
	s_nop 0
	v_mul_f32_e32 v24, v25, v24
	v_mul_f32_e32 v25, v18, v18
	v_fmac_f32_e32 v25, v0, v0
	v_add_f32_e32 v25, v25, v26
	v_mul_f32_e32 v26, v22, v22
	v_mul_f32_e32 v27, v24, v24
	v_fmac_f32_e32 v26, v21, v21
	v_fmac_f32_e32 v27, v23, v23
	v_add_f32_e32 v26, v26, v27
	v_add_f32_e32 v25, v25, v26
	v_add_f32_e32 v25, v38, v25
	v_cvt_pk_bf16_f32 v18, v0, v18
	v_mov_b32_e32 v0, v25
	s_nop 1
	v_permlane16_swap_b32_e32 v25, v0
	v_add_f32_e32 v0, v25, v0
	v_cvt_pk_bf16_f32 v19, v19, v20
	v_cvt_pk_bf16_f32 v20, v21, v22
	v_cvt_pk_bf16_f32 v21, v23, v24
	global_store_dwordx4 v[36:37], v[18:21], off offset:256 nt
	s_nop 1
	v_mov_b32_e32 v18, v0
	s_nop 1
	v_permlane32_swap_b32_e32 v0, v18
	s_and_saveexec_b64 s[0:1], s[2:3]
	s_cbranch_execz .LBB0_187
	v_add_f32_e32 v0, v0, v18
	v_lshlrev_b64 v[18:19], 7, v[34:35]
	s_lshl_b32 s36, s12, 2
	v_lshl_add_u64 v[18:19], v[138:139], 0, v[18:19]
	s_mov_b32 s37, s40
	v_lshl_add_u64 v[18:19], s[36:37], 2, v[18:19]
	s_lshl_b32 s36, s28, 2
	v_lshl_add_u64 v[18:19], v[18:19], 0, s[36:37]
	global_store_dword v[18:19], v0, off offset:-128
.LBB0_187:
	s_or_b64 exec, exec, s[0:1]
	v_add_f32_e32 v0, v157, v158
	v_fmamk_f32 v0, v0, 0x3a000000, v240
	v_rsq_f32_e32 v0, v0
	v_add_u32_e32 v18, 0xb0, v150
	v_ashrrev_i32_e32 v19, 31, v18
	v_lshlrev_b64 v[20:21], 13, v[18:19]
	v_pk_mul_f32 v[10:11], v[10:11], v[0:1] op_sel_hi:[1,0]
	v_pk_mul_f32 v[12:13], v[12:13], v[0:1] op_sel_hi:[1,0]
	v_mul_f32_e32 v23, 0x3d372713, v10
	v_mul_f32_e32 v22, 0x3fcc422a, v10
	v_fma_f32 v23, v10, v23, 1.0
	v_mul_f32_e32 v22, v22, v23
	v_mul_f32_e32 v22, 0xbfb8aa3b, v22
	v_exp_f32_e32 v22, v22
	v_mul_f32_e32 v23, 0x3d372713, v11
	v_fma_f32 v23, v11, v23, 1.0
	v_pk_mul_f32 v[14:15], v[14:15], v[0:1] op_sel_hi:[1,0]
	v_add_f32_e32 v22, 1.0, v22
	v_rcp_f32_e32 v22, v22
	v_pk_mul_f32 v[16:17], v[16:17], v[0:1] op_sel_hi:[1,0]
	v_lshl_add_u64 v[20:21], v[152:153], 0, v[20:21]
	v_pk_mul_f32 v[2:3], v[2:3], v[0:1] op_sel_hi:[1,0]
	v_mul_f32_e32 v10, v10, v22
	v_mul_f32_e32 v22, 0x3fcc422a, v11
	v_mul_f32_e32 v22, v22, v23
	v_mul_f32_e32 v22, 0xbfb8aa3b, v22
	v_exp_f32_e32 v22, v22
	v_mul_f32_e32 v23, 0x3d372713, v12
	v_fma_f32 v23, v12, v23, 1.0
	v_pk_mul_f32 v[4:5], v[4:5], v[0:1] op_sel_hi:[1,0]
	v_add_f32_e32 v22, 1.0, v22
	v_rcp_f32_e32 v22, v22
	v_pk_mul_f32 v[8:9], v[8:9], v[0:1] op_sel_hi:[1,0]
	v_pk_mul_f32 v[6:7], v[6:7], v[0:1] op_sel_hi:[1,0]
	v_mul_f32_e32 v0, 0x3fcc422a, v2
	v_mul_f32_e32 v11, v11, v22
	v_mul_f32_e32 v22, 0x3fcc422a, v12
	v_mul_f32_e32 v22, v22, v23
	v_mul_f32_e32 v22, 0xbfb8aa3b, v22
	v_exp_f32_e32 v22, v22
	v_mul_f32_e32 v23, 0x3d372713, v13
	v_fma_f32 v23, v13, v23, 1.0
	v_add_f32_e32 v22, 1.0, v22
	v_rcp_f32_e32 v22, v22
	s_nop 0
	v_mul_f32_e32 v12, v12, v22
	v_mul_f32_e32 v22, 0x3fcc422a, v13
	v_mul_f32_e32 v22, v22, v23
	v_mul_f32_e32 v22, 0xbfb8aa3b, v22
	v_exp_f32_e32 v22, v22
	v_mul_f32_e32 v23, 0x3d372713, v14
	v_fma_f32 v23, v14, v23, 1.0
	v_add_f32_e32 v22, 1.0, v22
	v_rcp_f32_e32 v22, v22
	s_nop 0
	v_mul_f32_e32 v13, v13, v22
	v_mul_f32_e32 v22, 0x3fcc422a, v14
	v_mul_f32_e32 v22, v22, v23
	v_mul_f32_e32 v22, 0xbfb8aa3b, v22
	v_exp_f32_e32 v22, v22
	v_mul_f32_e32 v23, 0x3d372713, v15
	v_fma_f32 v23, v15, v23, 1.0
	v_add_f32_e32 v22, 1.0, v22
	v_rcp_f32_e32 v22, v22
	s_nop 0
	v_mul_f32_e32 v14, v14, v22
	v_mul_f32_e32 v22, 0x3fcc422a, v15
	v_mul_f32_e32 v22, v22, v23
	v_mul_f32_e32 v22, 0xbfb8aa3b, v22
	v_exp_f32_e32 v22, v22
	v_mul_f32_e32 v23, 0x3d372713, v16
	v_fma_f32 v23, v16, v23, 1.0
	v_add_f32_e32 v22, 1.0, v22
	v_rcp_f32_e32 v22, v22
	s_nop 0
	v_mul_f32_e32 v15, v15, v22
	v_mul_f32_e32 v22, 0x3fcc422a, v16
	v_mul_f32_e32 v22, v22, v23
	v_mul_f32_e32 v22, 0xbfb8aa3b, v22
	v_exp_f32_e32 v22, v22
	v_mul_f32_e32 v23, 0x3d372713, v17
	v_fma_f32 v23, v17, v23, 1.0
	v_add_f32_e32 v22, 1.0, v22
	v_rcp_f32_e32 v22, v22
	s_nop 0
	v_mul_f32_e32 v16, v16, v22
	v_mul_f32_e32 v22, 0x3fcc422a, v17
	v_mul_f32_e32 v22, v22, v23
	v_mul_f32_e32 v22, 0xbfb8aa3b, v22
	v_exp_f32_e32 v22, v22
	v_mul_f32_e32 v23, v13, v13
	v_fmac_f32_e32 v23, v12, v12
	v_add_f32_e32 v22, 1.0, v22
	v_rcp_f32_e32 v22, v22
	s_nop 0
	v_mul_f32_e32 v17, v17, v22
	v_mul_f32_e32 v22, v11, v11
	v_fmac_f32_e32 v22, v10, v10
	v_cvt_pk_bf16_f32 v10, v10, v11
	v_cvt_pk_bf16_f32 v11, v12, v13
	v_cvt_pk_bf16_f32 v12, v14, v15
	v_cvt_pk_bf16_f32 v13, v16, v17
	global_store_dwordx4 v[20:21], v[10:13], off nt
	v_add_f32_e32 v22, v22, v23
	v_mul_f32_e32 v23, v15, v15
	v_mul_f32_e32 v10, 0x3d372713, v2
	v_fma_f32 v10, v2, v10, 1.0
	v_mul_f32_e32 v0, v0, v10
	v_mul_f32_e32 v0, 0xbfb8aa3b, v0
	v_exp_f32_e32 v0, v0
	v_mul_f32_e32 v10, 0x3d372713, v3
	v_fma_f32 v10, v3, v10, 1.0
	v_mul_f32_e32 v24, v17, v17
	v_add_f32_e32 v0, 1.0, v0
	v_rcp_f32_e32 v0, v0
	v_fmac_f32_e32 v23, v14, v14
	v_fmac_f32_e32 v24, v16, v16
	v_add_f32_e32 v23, v23, v24
	v_mul_f32_e32 v0, v2, v0
	v_mul_f32_e32 v2, 0x3fcc422a, v3
	v_mul_f32_e32 v2, v2, v10
	v_mul_f32_e32 v2, 0xbfb8aa3b, v2
	v_exp_f32_e32 v2, v2
	v_mul_f32_e32 v10, 0x3d372713, v4
	v_fma_f32 v10, v4, v10, 1.0
	v_add_f32_e32 v22, v22, v23
	v_add_f32_e32 v2, 1.0, v2
	v_rcp_f32_e32 v2, v2
	s_nop 0
	v_mul_f32_e32 v2, v3, v2
	v_mul_f32_e32 v3, 0x3fcc422a, v4
	v_mul_f32_e32 v3, v3, v10
	v_mul_f32_e32 v3, 0xbfb8aa3b, v3
	v_exp_f32_e32 v3, v3
	v_mul_f32_e32 v10, 0x3d372713, v5
	v_fma_f32 v10, v5, v10, 1.0
	v_add_f32_e32 v3, 1.0, v3
	v_rcp_f32_e32 v3, v3
	s_nop 0
	v_mul_f32_e32 v3, v4, v3
	v_mul_f32_e32 v4, 0x3fcc422a, v5
	v_mul_f32_e32 v4, v4, v10
	v_mul_f32_e32 v4, 0xbfb8aa3b, v4
	v_exp_f32_e32 v4, v4
	v_mul_f32_e32 v10, 0x3d372713, v6
	v_fma_f32 v10, v6, v10, 1.0
	v_add_f32_e32 v4, 1.0, v4
	v_rcp_f32_e32 v4, v4
	s_nop 0
	v_mul_f32_e32 v4, v5, v4
	v_mul_f32_e32 v5, 0x3fcc422a, v6
	v_mul_f32_e32 v5, v5, v10
	v_mul_f32_e32 v5, 0xbfb8aa3b, v5
	v_exp_f32_e32 v5, v5
	v_mul_f32_e32 v10, 0x3d372713, v7
	v_fma_f32 v10, v7, v10, 1.0
	v_add_f32_e32 v5, 1.0, v5
	v_rcp_f32_e32 v5, v5
	s_nop 0
	v_mul_f32_e32 v5, v6, v5
	v_mul_f32_e32 v6, 0x3fcc422a, v7
	v_mul_f32_e32 v6, v6, v10
	v_mul_f32_e32 v6, 0xbfb8aa3b, v6
	v_exp_f32_e32 v6, v6
	v_mul_f32_e32 v10, 0x3d372713, v8
	v_fma_f32 v10, v8, v10, 1.0
	v_add_f32_e32 v6, 1.0, v6
	v_rcp_f32_e32 v6, v6
	s_nop 0
	v_mul_f32_e32 v6, v7, v6
	v_mul_f32_e32 v7, 0x3fcc422a, v8
	v_mul_f32_e32 v7, v7, v10
	v_mul_f32_e32 v7, 0xbfb8aa3b, v7
	v_exp_f32_e32 v7, v7
	v_mul_f32_e32 v10, 0x3d372713, v9
	v_fma_f32 v10, v9, v10, 1.0
	v_add_f32_e32 v7, 1.0, v7
	v_rcp_f32_e32 v7, v7
	s_nop 0
	v_mul_f32_e32 v7, v8, v7
	v_mul_f32_e32 v8, 0x3fcc422a, v9
	v_mul_f32_e32 v8, v8, v10
	v_mul_f32_e32 v8, 0xbfb8aa3b, v8
	v_exp_f32_e32 v8, v8
	v_mul_f32_e32 v10, v4, v4
	v_fmac_f32_e32 v10, v3, v3
	v_add_f32_e32 v8, 1.0, v8
	v_rcp_f32_e32 v8, v8
	s_nop 0
	v_mul_f32_e32 v8, v9, v8
	v_mul_f32_e32 v9, v2, v2
	v_fmac_f32_e32 v9, v0, v0
	v_add_f32_e32 v9, v9, v10
	v_mul_f32_e32 v10, v6, v6
	v_mul_f32_e32 v11, v8, v8
	v_fmac_f32_e32 v10, v5, v5
	v_fmac_f32_e32 v11, v7, v7
	v_add_f32_e32 v10, v10, v11
	v_add_f32_e32 v9, v9, v10
	v_add_f32_e32 v9, v22, v9
	v_cvt_pk_bf16_f32 v2, v0, v2
	v_mov_b32_e32 v0, v9
	s_nop 1
	v_permlane16_swap_b32_e32 v9, v0
	v_add_f32_e32 v0, v9, v0
	v_cvt_pk_bf16_f32 v3, v3, v4
	v_cvt_pk_bf16_f32 v4, v5, v6
	v_cvt_pk_bf16_f32 v5, v7, v8
	global_store_dwordx4 v[20:21], v[2:5], off offset:256 nt
	s_nop 1
	v_mov_b32_e32 v2, v0
	s_nop 1
	v_permlane32_swap_b32_e32 v0, v2
	s_and_saveexec_b64 s[0:1], s[2:3]
	s_cbranch_execz .LBB0_189
	v_add_f32_e32 v0, v0, v2
	v_lshlrev_b64 v[2:3], 7, v[18:19]
	s_lshl_b32 s2, s12, 2
	v_lshl_add_u64 v[2:3], v[138:139], 0, v[2:3]
	s_mov_b32 s3, s40
	v_lshl_add_u64 v[2:3], s[2:3], 2, v[2:3]
	s_lshl_b32 s2, s28, 2
	v_lshl_add_u64 v[2:3], v[2:3], 0, s[2:3]
	global_store_dword v[2:3], v0, off offset:-128

.Lalign_skip_1:
	v_mov_b32_e32 v151, v150
	s_nop 1
	v_permlane16_swap_b32_e32 v150, v151
	v_add_f32_e32 v161, v150, v151
	v_lshlrev_b32_e32 v150, 16, v176
	v_and_b32_e32 v151, 0xffff0000, v176
	v_add_f32_e32 v150, v150, v151
	v_lshlrev_b32_e32 v151, 16, v177
	v_and_b32_e32 v154, 0xffff0000, v177
	v_add_f32_e32 v151, v151, v154
	v_add_f32_e32 v150, v150, v151
	v_lshlrev_b32_e32 v151, 16, v178
	v_and_b32_e32 v154, 0xffff0000, v178
	v_add_f32_e32 v151, v151, v154
	v_lshlrev_b32_e32 v154, 16, v179
	v_and_b32_e32 v155, 0xffff0000, v179
	v_add_f32_e32 v154, v154, v155
	ds_read_b128 v[176:179], v167 offset:10240
	ds_read_b128 v[180:183], v167 offset:11264
	v_add_f32_e32 v151, v151, v154
	v_add_f32_e32 v150, v150, v151
	v_mov_b32_e32 v151, v150
	s_nop 1
	v_permlane16_swap_b32_e32 v150, v151
	v_add_f32_e32 v159, v150, v151
	s_waitcnt lgkmcnt(0)
	v_lshlrev_b32_e32 v150, 16, v176
	v_and_b32_e32 v151, 0xffff0000, v176
	v_add_f32_e32 v150, v150, v151
	v_lshlrev_b32_e32 v151, 16, v177
	v_and_b32_e32 v154, 0xffff0000, v177
	v_add_f32_e32 v151, v151, v154
	v_add_f32_e32 v150, v150, v151
	v_lshlrev_b32_e32 v151, 16, v178
	v_and_b32_e32 v154, 0xffff0000, v178
	v_add_f32_e32 v151, v151, v154
	v_lshlrev_b32_e32 v154, 16, v179
	v_and_b32_e32 v155, 0xffff0000, v179
	v_add_f32_e32 v154, v154, v155
	v_add_f32_e32 v151, v151, v154
	v_add_f32_e32 v150, v150, v151
	v_mov_b32_e32 v151, v150
	s_nop 1
	v_permlane16_swap_b32_e32 v150, v151
	v_add_f32_e32 v157, v150, v151
	v_lshlrev_b32_e32 v150, 16, v180
	v_and_b32_e32 v151, 0xffff0000, v180
	v_add_f32_e32 v150, v150, v151
	v_lshlrev_b32_e32 v151, 16, v181
	v_and_b32_e32 v154, 0xffff0000, v181
	v_add_f32_e32 v151, v151, v154
	v_add_f32_e32 v150, v150, v151
	v_lshlrev_b32_e32 v151, 16, v182
	v_and_b32_e32 v154, 0xffff0000, v182
	v_add_f32_e32 v151, v151, v154
	v_lshlrev_b32_e32 v154, 16, v183
	v_and_b32_e32 v155, 0xffff0000, v183
	v_add_f32_e32 v154, v154, v155
	s_lshl_b32 s13, s2, 8
	s_mul_i32 s8, s15, 0xfffff400
	v_add_f32_e32 v151, v151, v154
	s_add_i32 s8, s8, s13
	v_add_f32_e32 v150, v150, v151
	v_fmamk_f32 v0, v0, 0x3a000000, v240
	v_mov_b32_e32 v151, v150
	v_or_b32_e32 v176, s8, v165
	v_rsq_f32_e32 v0, v0
	v_permlane16_swap_b32_e32 v150, v151
	v_ashrrev_i32_e32 v177, 31, v176
	v_add_f32_e32 v154, v150, v151
	v_add_u32_e32 v150, s3, v156
	v_lshl_add_u64 v[152:153], v[176:177], 1, v[152:153]
	s_movk_i32 s3, 0x1800
	v_mad_i64_i32 v[180:181], s[8:9], v150, s3, v[152:153]
	s_and_b32 s3, s2, -4
	v_mov_b32_e32 v174, v173
	v_mov_b32_e32 v172, v171
	v_mov_b32_e32 v170, v169
	v_mov_b32_e32 v168, v161
	v_mov_b32_e32 v160, v159
	v_mov_b32_e32 v158, v157
	v_mov_b32_e32 v155, v154
	s_cmp_eq_u32 s3, 4
	v_permlane32_swap_b32_e32 v173, v174
	v_permlane32_swap_b32_e32 v171, v172
	v_permlane32_swap_b32_e32 v169, v170
	v_permlane32_swap_b32_e32 v161, v168
	v_permlane32_swap_b32_e32 v159, v160
	v_permlane32_swap_b32_e32 v157, v158
	v_permlane32_swap_b32_e32 v154, v155
	v_ashrrev_i32_e32 v151, 31, v150
	v_pk_mul_f32 v[128:129], v[128:129], v[0:1] op_sel_hi:[1,0]
	v_pk_mul_f32 v[126:127], v[126:127], v[0:1] op_sel_hi:[1,0]
	v_pk_mul_f32 v[124:125], v[124:125], v[0:1] op_sel_hi:[1,0]
	v_pk_mul_f32 v[122:123], v[122:123], v[0:1] op_sel_hi:[1,0]
	v_cvt_pk_bf16_f32 v176, v126, v127
	v_cvt_pk_bf16_f32 v177, v128, v129
	v_pk_mul_f32 v[120:121], v[120:121], v[0:1] op_sel_hi:[1,0]
	v_cvt_pk_bf16_f32 v178, v122, v123
	v_cvt_pk_bf16_f32 v179, v124, v125
	v_pk_mul_f32 v[118:119], v[118:119], v[0:1] op_sel_hi:[1,0]
	v_pk_mul_f32 v[116:117], v[116:117], v[0:1] op_sel_hi:[1,0]
	v_pk_mul_f32 v[114:115], v[114:115], v[0:1] op_sel_hi:[1,0]
	s_cselect_b64 s[16:17], -1, 0
	s_cmp_lg_u32 s3, 4
	global_store_dwordx4 v[180:181], v[176:179], off nt
	s_nop 1
	v_cvt_pk_bf16_f32 v176, v118, v119
	v_cvt_pk_bf16_f32 v177, v120, v121
	v_cvt_pk_bf16_f32 v178, v114, v115
	v_cvt_pk_bf16_f32 v179, v116, v117
	global_store_dwordx4 v[180:181], v[176:179], off offset:256 nt
	s_cbranch_scc1 .LBB0_514
	v_mul_f32_e32 v0, v127, v127
	v_mul_f32_e32 v123, v123, v123
	v_mul_f32_e32 v119, v119, v119
	v_mul_f32_e32 v115, v115, v115
	v_fmac_f32_e32 v0, v126, v126
	v_mul_f32_e32 v126, v129, v129
	v_fmac_f32_e32 v123, v122, v122
	v_mul_f32_e32 v122, v125, v125
	v_fmac_f32_e32 v119, v118, v118
	v_mul_f32_e32 v118, v121, v121
	v_fmac_f32_e32 v115, v114, v114
	v_mul_f32_e32 v114, v117, v117
	v_fmac_f32_e32 v126, v128, v128
	v_fmac_f32_e32 v122, v124, v124
	v_fmac_f32_e32 v118, v120, v120
	v_fmac_f32_e32 v114, v116, v116
	v_add_f32_e32 v0, v0, v126
	v_add_f32_e32 v122, v123, v122
	v_add_f32_e32 v118, v119, v118
	v_add_f32_e32 v114, v115, v114
	v_add_f32_e32 v0, v0, v122
	v_add_f32_e32 v115, v118, v114
	v_mov_b32_e32 v114, v0
	v_mov_b32_e32 v116, v115
	s_nop 0
	v_permlane16_swap_b32_e32 v0, v114
	v_permlane16_swap_b32_e32 v115, v116
	v_add_f32_e32 v0, v0, v114
	v_add_f32_e32 v115, v115, v116
	v_mov_b32_e32 v114, v0
	v_mov_b32_e32 v116, v115
	s_nop 0
	v_permlane32_swap_b32_e32 v0, v114
	v_permlane32_swap_b32_e32 v115, v116
	s_and_saveexec_b64 s[8:9], s[4:5]
	s_cbranch_execz .LBB0_513
	v_add_f32_e32 v116, v115, v116
	v_add_f32_e32 v0, v0, v114
	v_lshlrev_b64 v[114:115], 7, v[150:151]
	v_lshl_add_u64 v[114:115], v[138:139], 0, v[114:115]
	s_lshl_b32 s36, s2, 3
	s_mov_b32 s37, s40
	v_lshl_add_u64 v[114:115], s[36:37], 2, v[114:115]
	s_lshl_b32 s36, s27, 2
	v_lshl_add_u64 v[114:115], v[114:115], 0, s[36:37]
	global_store_dword v[114:115], v0, off offset:-128
	global_store_dword v[114:115], v116, off offset:-112

.LBB0_514:
	v_add_f32_e32 v0, v173, v174
	v_fmamk_f32 v0, v0, 0x3a000000, v240
	v_rsq_f32_e32 v0, v0
	v_or_b32_e32 v114, 16, v150
	s_movk_i32 s3, 0x1800
	v_mad_i64_i32 v[120:121], s[8:9], v114, s3, v[152:153]
	v_pk_mul_f32 v[112:113], v[112:113], v[0:1] op_sel_hi:[1,0]
	v_pk_mul_f32 v[110:111], v[110:111], v[0:1] op_sel_hi:[1,0]
	v_pk_mul_f32 v[108:109], v[108:109], v[0:1] op_sel_hi:[1,0]
	v_pk_mul_f32 v[106:107], v[106:107], v[0:1] op_sel_hi:[1,0]
	v_pk_mul_f32 v[104:105], v[104:105], v[0:1] op_sel_hi:[1,0]
	v_pk_mul_f32 v[102:103], v[102:103], v[0:1] op_sel_hi:[1,0]
	v_pk_mul_f32 v[100:101], v[100:101], v[0:1] op_sel_hi:[1,0]
	v_pk_mul_f32 v[98:99], v[98:99], v[0:1] op_sel_hi:[1,0]
	v_cndmask_b32_e64 v0, 0, 1, s[16:17]
	v_cvt_pk_bf16_f32 v116, v110, v111
	v_cvt_pk_bf16_f32 v117, v112, v113
	v_cvt_pk_bf16_f32 v118, v106, v107
	v_cvt_pk_bf16_f32 v119, v108, v109
	v_cmp_ne_u32_e64 s[8:9], 1, v0
	s_andn2_b64 vcc, exec, s[16:17]
	global_store_dwordx4 v[120:121], v[116:119], off nt
	s_nop 1
	v_cvt_pk_bf16_f32 v116, v102, v103
	v_cvt_pk_bf16_f32 v117, v104, v105
	v_cvt_pk_bf16_f32 v118, v98, v99
	v_cvt_pk_bf16_f32 v119, v100, v101
	global_store_dwordx4 v[120:121], v[116:119], off offset:256 nt
	s_cbranch_vccnz .LBB0_518
	v_mul_f32_e32 v0, v111, v111
	v_mul_f32_e32 v107, v107, v107
	v_mul_f32_e32 v103, v103, v103
	v_mul_f32_e32 v99, v99, v99
	v_fmac_f32_e32 v0, v110, v110
	v_mul_f32_e32 v110, v113, v113
	v_fmac_f32_e32 v107, v106, v106
	v_mul_f32_e32 v106, v109, v109
	v_fmac_f32_e32 v103, v102, v102
	v_mul_f32_e32 v102, v105, v105
	v_fmac_f32_e32 v99, v98, v98
	v_mul_f32_e32 v98, v101, v101
	v_fmac_f32_e32 v110, v112, v112
	v_fmac_f32_e32 v106, v108, v108
	v_fmac_f32_e32 v102, v104, v104
	v_fmac_f32_e32 v98, v100, v100
	v_add_f32_e32 v0, v0, v110
	v_add_f32_e32 v106, v107, v106
	v_add_f32_e32 v102, v103, v102
	v_add_f32_e32 v98, v99, v98
	v_add_f32_e32 v0, v0, v106
	v_add_f32_e32 v99, v102, v98
	v_mov_b32_e32 v98, v0
	v_mov_b32_e32 v100, v99
	s_nop 0
	v_permlane16_swap_b32_e32 v0, v98
	v_permlane16_swap_b32_e32 v99, v100
	v_add_f32_e32 v0, v0, v98
	v_add_f32_e32 v99, v99, v100
	v_mov_b32_e32 v98, v0
	v_mov_b32_e32 v100, v99
	s_nop 0
	v_permlane32_swap_b32_e32 v0, v98
	v_permlane32_swap_b32_e32 v99, v100
	s_and_saveexec_b64 s[16:17], s[4:5]
	s_cbranch_execz .LBB0_517
	v_ashrrev_i32_e32 v115, 31, v114
	v_add_f32_e32 v100, v99, v100
	v_add_f32_e32 v0, v0, v98
	v_lshlrev_b64 v[98:99], 7, v[114:115]
	v_lshl_add_u64 v[98:99], v[138:139], 0, v[98:99]
	s_lshl_b32 s36, s2, 3
	s_mov_b32 s37, s40
	v_lshl_add_u64 v[98:99], s[36:37], 2, v[98:99]
	s_lshl_b32 s36, s27, 2
	v_lshl_add_u64 v[98:99], v[98:99], 0, s[36:37]
	global_store_dword v[98:99], v0, off offset:-128
	global_store_dword v[98:99], v100, off offset:-112

.LBB0_518:
	v_add_f32_e32 v0, v171, v172
	v_fmamk_f32 v0, v0, 0x3a000000, v240
	v_rsq_f32_e32 v0, v0
	v_or_b32_e32 v98, 32, v150
	v_mad_i64_i32 v[104:105], s[16:17], v98, s3, v[152:153]
	v_pk_mul_f32 v[96:97], v[96:97], v[0:1] op_sel_hi:[1,0]
	v_pk_mul_f32 v[94:95], v[94:95], v[0:1] op_sel_hi:[1,0]
	v_pk_mul_f32 v[92:93], v[92:93], v[0:1] op_sel_hi:[1,0]
	v_pk_mul_f32 v[90:91], v[90:91], v[0:1] op_sel_hi:[1,0]
	v_cvt_pk_bf16_f32 v100, v94, v95
	v_cvt_pk_bf16_f32 v101, v96, v97
	v_pk_mul_f32 v[88:89], v[88:89], v[0:1] op_sel_hi:[1,0]
	v_cvt_pk_bf16_f32 v102, v90, v91
	v_cvt_pk_bf16_f32 v103, v92, v93
	v_pk_mul_f32 v[86:87], v[86:87], v[0:1] op_sel_hi:[1,0]
	v_pk_mul_f32 v[84:85], v[84:85], v[0:1] op_sel_hi:[1,0]
	v_pk_mul_f32 v[82:83], v[82:83], v[0:1] op_sel_hi:[1,0]
	s_and_b64 vcc, exec, s[8:9]
	global_store_dwordx4 v[104:105], v[100:103], off nt
	s_nop 1
	v_cvt_pk_bf16_f32 v100, v86, v87
	v_cvt_pk_bf16_f32 v101, v88, v89
	v_cvt_pk_bf16_f32 v102, v82, v83
	v_cvt_pk_bf16_f32 v103, v84, v85
	global_store_dwordx4 v[104:105], v[100:103], off offset:256 nt
	s_cbranch_vccnz .LBB0_522
	v_mul_f32_e32 v0, v95, v95
	v_mul_f32_e32 v91, v91, v91
	v_mul_f32_e32 v87, v87, v87
	v_mul_f32_e32 v83, v83, v83
	v_fmac_f32_e32 v0, v94, v94
	v_mul_f32_e32 v94, v97, v97
	v_fmac_f32_e32 v91, v90, v90
	v_mul_f32_e32 v90, v93, v93
	v_fmac_f32_e32 v87, v86, v86
	v_mul_f32_e32 v86, v89, v89
	v_fmac_f32_e32 v83, v82, v82
	v_mul_f32_e32 v82, v85, v85
	v_fmac_f32_e32 v94, v96, v96
	v_fmac_f32_e32 v90, v92, v92
	v_fmac_f32_e32 v86, v88, v88
	v_fmac_f32_e32 v82, v84, v84
	v_add_f32_e32 v0, v0, v94
	v_add_f32_e32 v90, v91, v90
	v_add_f32_e32 v86, v87, v86
	v_add_f32_e32 v82, v83, v82
	v_add_f32_e32 v0, v0, v90
	v_add_f32_e32 v83, v86, v82
	v_mov_b32_e32 v82, v0
	v_mov_b32_e32 v84, v83
	s_nop 0
	v_permlane16_swap_b32_e32 v0, v82
	v_permlane16_swap_b32_e32 v83, v84
	v_add_f32_e32 v0, v0, v82
	v_add_f32_e32 v83, v83, v84
	v_mov_b32_e32 v82, v0
	v_mov_b32_e32 v84, v83
	s_nop 0
	v_permlane32_swap_b32_e32 v0, v82
	v_permlane32_swap_b32_e32 v83, v84
	s_and_saveexec_b64 s[16:17], s[4:5]
	s_cbranch_execz .LBB0_521
	v_ashrrev_i32_e32 v99, 31, v98
	v_add_f32_e32 v84, v83, v84
	v_add_f32_e32 v0, v0, v82
	v_lshlrev_b64 v[82:83], 7, v[98:99]
	v_lshl_add_u64 v[82:83], v[138:139], 0, v[82:83]
	s_lshl_b32 s36, s2, 3
	s_mov_b32 s37, s40
	v_lshl_add_u64 v[82:83], s[36:37], 2, v[82:83]
	s_lshl_b32 s36, s27, 2
	v_lshl_add_u64 v[82:83], v[82:83], 0, s[36:37]
	global_store_dword v[82:83], v0, off offset:-128
	global_store_dword v[82:83], v84, off offset:-112

.LBB0_522:
	v_add_f32_e32 v0, v169, v170
	v_fmamk_f32 v0, v0, 0x3a000000, v240
	v_rsq_f32_e32 v0, v0
	v_or_b32_e32 v82, 48, v150
	v_mad_i64_i32 v[88:89], s[16:17], v82, s3, v[152:153]
	v_pk_mul_f32 v[80:81], v[80:81], v[0:1] op_sel_hi:[1,0]
	v_pk_mul_f32 v[78:79], v[78:79], v[0:1] op_sel_hi:[1,0]
	v_pk_mul_f32 v[76:77], v[76:77], v[0:1] op_sel_hi:[1,0]
	v_pk_mul_f32 v[74:75], v[74:75], v[0:1] op_sel_hi:[1,0]
	v_cvt_pk_bf16_f32 v84, v78, v79
	v_cvt_pk_bf16_f32 v85, v80, v81
	v_pk_mul_f32 v[72:73], v[72:73], v[0:1] op_sel_hi:[1,0]
	v_cvt_pk_bf16_f32 v86, v74, v75
	v_cvt_pk_bf16_f32 v87, v76, v77
	v_pk_mul_f32 v[70:71], v[70:71], v[0:1] op_sel_hi:[1,0]
	v_pk_mul_f32 v[68:69], v[68:69], v[0:1] op_sel_hi:[1,0]
	v_pk_mul_f32 v[66:67], v[66:67], v[0:1] op_sel_hi:[1,0]
	s_and_b64 vcc, exec, s[8:9]
	global_store_dwordx4 v[88:89], v[84:87], off nt
	s_nop 1
	v_cvt_pk_bf16_f32 v84, v70, v71
	v_cvt_pk_bf16_f32 v85, v72, v73
	v_cvt_pk_bf16_f32 v86, v66, v67
	v_cvt_pk_bf16_f32 v87, v68, v69
	global_store_dwordx4 v[88:89], v[84:87], off offset:256 nt
	s_cbranch_vccnz .LBB0_526
	v_mul_f32_e32 v0, v79, v79
	v_mul_f32_e32 v75, v75, v75
	v_mul_f32_e32 v71, v71, v71
	v_mul_f32_e32 v67, v67, v67
	v_fmac_f32_e32 v0, v78, v78
	v_mul_f32_e32 v78, v81, v81
	v_fmac_f32_e32 v75, v74, v74
	v_mul_f32_e32 v74, v77, v77
	v_fmac_f32_e32 v71, v70, v70
	v_mul_f32_e32 v70, v73, v73
	v_fmac_f32_e32 v67, v66, v66
	v_mul_f32_e32 v66, v69, v69
	v_fmac_f32_e32 v78, v80, v80
	v_fmac_f32_e32 v74, v76, v76
	v_fmac_f32_e32 v70, v72, v72
	v_fmac_f32_e32 v66, v68, v68
	v_add_f32_e32 v0, v0, v78
	v_add_f32_e32 v74, v75, v74
	v_add_f32_e32 v70, v71, v70
	v_add_f32_e32 v66, v67, v66
	v_add_f32_e32 v0, v0, v74
	v_add_f32_e32 v67, v70, v66
	v_mov_b32_e32 v66, v0
	v_mov_b32_e32 v68, v67
	s_nop 0
	v_permlane16_swap_b32_e32 v0, v66
	v_permlane16_swap_b32_e32 v67, v68
	v_add_f32_e32 v0, v0, v66
	v_add_f32_e32 v67, v67, v68
	v_mov_b32_e32 v66, v0
	v_mov_b32_e32 v68, v67
	s_nop 0
	v_permlane32_swap_b32_e32 v0, v66
	v_permlane32_swap_b32_e32 v67, v68
	s_and_saveexec_b64 s[16:17], s[4:5]
	s_cbranch_execz .LBB0_525
	v_ashrrev_i32_e32 v83, 31, v82
	v_add_f32_e32 v68, v67, v68
	v_add_f32_e32 v0, v0, v66
	v_lshlrev_b64 v[66:67], 7, v[82:83]
	v_lshl_add_u64 v[66:67], v[138:139], 0, v[66:67]
	s_lshl_b32 s36, s2, 3
	s_mov_b32 s37, s40
	v_lshl_add_u64 v[66:67], s[36:37], 2, v[66:67]
	s_lshl_b32 s36, s27, 2
	v_lshl_add_u64 v[66:67], v[66:67], 0, s[36:37]
	global_store_dword v[66:67], v0, off offset:-128
	global_store_dword v[66:67], v68, off offset:-112

.LBB0_526:
	v_add_f32_e32 v0, v161, v168
	v_fmamk_f32 v0, v0, 0x3a000000, v240
	v_rsq_f32_e32 v0, v0
	v_add_u32_e32 v66, 0x80, v150
	v_mad_i64_i32 v[72:73], s[16:17], v66, s3, v[152:153]
	v_pk_mul_f32 v[64:65], v[64:65], v[0:1] op_sel_hi:[1,0]
	v_pk_mul_f32 v[62:63], v[62:63], v[0:1] op_sel_hi:[1,0]
	v_pk_mul_f32 v[60:61], v[60:61], v[0:1] op_sel_hi:[1,0]
	v_pk_mul_f32 v[58:59], v[58:59], v[0:1] op_sel_hi:[1,0]
	v_cvt_pk_bf16_f32 v68, v62, v63
	v_cvt_pk_bf16_f32 v69, v64, v65
	v_pk_mul_f32 v[56:57], v[56:57], v[0:1] op_sel_hi:[1,0]
	v_cvt_pk_bf16_f32 v70, v58, v59
	v_cvt_pk_bf16_f32 v71, v60, v61
	v_pk_mul_f32 v[54:55], v[54:55], v[0:1] op_sel_hi:[1,0]
	v_pk_mul_f32 v[52:53], v[52:53], v[0:1] op_sel_hi:[1,0]
	v_pk_mul_f32 v[50:51], v[50:51], v[0:1] op_sel_hi:[1,0]
	s_and_b64 vcc, exec, s[8:9]
	global_store_dwordx4 v[72:73], v[68:71], off nt
	s_nop 1
	v_cvt_pk_bf16_f32 v68, v54, v55
	v_cvt_pk_bf16_f32 v69, v56, v57
	v_cvt_pk_bf16_f32 v70, v50, v51
	v_cvt_pk_bf16_f32 v71, v52, v53
	global_store_dwordx4 v[72:73], v[68:71], off offset:256 nt
	s_cbranch_vccnz .LBB0_530
	v_mul_f32_e32 v0, v63, v63
	v_mul_f32_e32 v59, v59, v59
	v_mul_f32_e32 v55, v55, v55
	v_mul_f32_e32 v51, v51, v51
	v_fmac_f32_e32 v0, v62, v62
	v_mul_f32_e32 v62, v65, v65
	v_fmac_f32_e32 v59, v58, v58
	v_mul_f32_e32 v58, v61, v61
	v_fmac_f32_e32 v55, v54, v54
	v_mul_f32_e32 v54, v57, v57
	v_fmac_f32_e32 v51, v50, v50
	v_mul_f32_e32 v50, v53, v53
	v_fmac_f32_e32 v62, v64, v64
	v_fmac_f32_e32 v58, v60, v60
	v_fmac_f32_e32 v54, v56, v56
	v_fmac_f32_e32 v50, v52, v52
	v_add_f32_e32 v0, v0, v62
	v_add_f32_e32 v58, v59, v58
	v_add_f32_e32 v54, v55, v54
	v_add_f32_e32 v50, v51, v50
	v_add_f32_e32 v0, v0, v58
	v_add_f32_e32 v51, v54, v50
	v_mov_b32_e32 v50, v0
	v_mov_b32_e32 v52, v51
	s_nop 0
	v_permlane16_swap_b32_e32 v0, v50
	v_permlane16_swap_b32_e32 v51, v52
	v_add_f32_e32 v0, v0, v50
	v_add_f32_e32 v51, v51, v52
	v_mov_b32_e32 v50, v0
	v_mov_b32_e32 v52, v51
	s_nop 0
	v_permlane32_swap_b32_e32 v0, v50
	v_permlane32_swap_b32_e32 v51, v52
	s_and_saveexec_b64 s[16:17], s[4:5]
	s_cbranch_execz .LBB0_529
	v_ashrrev_i32_e32 v67, 31, v66
	v_add_f32_e32 v52, v51, v52
	v_add_f32_e32 v0, v0, v50
	v_lshlrev_b64 v[50:51], 7, v[66:67]
	v_lshl_add_u64 v[50:51], v[138:139], 0, v[50:51]
	s_lshl_b32 s36, s2, 3
	s_mov_b32 s37, s40
	v_lshl_add_u64 v[50:51], s[36:37], 2, v[50:51]
	s_lshl_b32 s36, s27, 2
	v_lshl_add_u64 v[50:51], v[50:51], 0, s[36:37]
	global_store_dword v[50:51], v0, off offset:-128
	global_store_dword v[50:51], v52, off offset:-112

.LBB0_530:
	v_add_f32_e32 v0, v159, v160
	v_fmamk_f32 v0, v0, 0x3a000000, v240
	v_rsq_f32_e32 v0, v0
	v_add_u32_e32 v50, 0x90, v150
	v_mad_i64_i32 v[56:57], s[16:17], v50, s3, v[152:153]
	v_pk_mul_f32 v[48:49], v[48:49], v[0:1] op_sel_hi:[1,0]
	v_pk_mul_f32 v[46:47], v[46:47], v[0:1] op_sel_hi:[1,0]
	v_pk_mul_f32 v[44:45], v[44:45], v[0:1] op_sel_hi:[1,0]
	v_pk_mul_f32 v[42:43], v[42:43], v[0:1] op_sel_hi:[1,0]
	v_cvt_pk_bf16_f32 v52, v46, v47
	v_cvt_pk_bf16_f32 v53, v48, v49
	v_pk_mul_f32 v[40:41], v[40:41], v[0:1] op_sel_hi:[1,0]
	v_cvt_pk_bf16_f32 v54, v42, v43
	v_cvt_pk_bf16_f32 v55, v44, v45
	v_pk_mul_f32 v[38:39], v[38:39], v[0:1] op_sel_hi:[1,0]
	v_pk_mul_f32 v[36:37], v[36:37], v[0:1] op_sel_hi:[1,0]
	v_pk_mul_f32 v[34:35], v[34:35], v[0:1] op_sel_hi:[1,0]
	s_and_b64 vcc, exec, s[8:9]
	global_store_dwordx4 v[56:57], v[52:55], off nt
	s_nop 1
	v_cvt_pk_bf16_f32 v52, v38, v39
	v_cvt_pk_bf16_f32 v53, v40, v41
	v_cvt_pk_bf16_f32 v54, v34, v35
	v_cvt_pk_bf16_f32 v55, v36, v37
	global_store_dwordx4 v[56:57], v[52:55], off offset:256 nt
	s_cbranch_vccnz .LBB0_534
	v_mul_f32_e32 v0, v47, v47
	v_mul_f32_e32 v43, v43, v43
	v_mul_f32_e32 v39, v39, v39
	v_mul_f32_e32 v35, v35, v35
	v_fmac_f32_e32 v0, v46, v46
	v_mul_f32_e32 v46, v49, v49
	v_fmac_f32_e32 v43, v42, v42
	v_mul_f32_e32 v42, v45, v45
	v_fmac_f32_e32 v39, v38, v38
	v_mul_f32_e32 v38, v41, v41
	v_fmac_f32_e32 v35, v34, v34
	v_mul_f32_e32 v34, v37, v37
	v_fmac_f32_e32 v46, v48, v48
	v_fmac_f32_e32 v42, v44, v44
	v_fmac_f32_e32 v38, v40, v40
	v_fmac_f32_e32 v34, v36, v36
	v_add_f32_e32 v0, v0, v46
	v_add_f32_e32 v42, v43, v42
	v_add_f32_e32 v38, v39, v38
	v_add_f32_e32 v34, v35, v34
	v_add_f32_e32 v0, v0, v42
	v_add_f32_e32 v35, v38, v34
	v_mov_b32_e32 v34, v0
	v_mov_b32_e32 v36, v35
	s_nop 0
	v_permlane16_swap_b32_e32 v0, v34
	v_permlane16_swap_b32_e32 v35, v36
	v_add_f32_e32 v0, v0, v34
	v_add_f32_e32 v35, v35, v36
	v_mov_b32_e32 v34, v0
	v_mov_b32_e32 v36, v35
	s_nop 0
	v_permlane32_swap_b32_e32 v0, v34
	v_permlane32_swap_b32_e32 v35, v36
	s_and_saveexec_b64 s[16:17], s[4:5]
	s_cbranch_execz .LBB0_533
	v_ashrrev_i32_e32 v51, 31, v50
	v_add_f32_e32 v36, v35, v36
	v_add_f32_e32 v0, v0, v34
	v_lshlrev_b64 v[34:35], 7, v[50:51]
	v_lshl_add_u64 v[34:35], v[138:139], 0, v[34:35]
	s_lshl_b32 s36, s2, 3
	s_mov_b32 s37, s40
	v_lshl_add_u64 v[34:35], s[36:37], 2, v[34:35]
	s_lshl_b32 s36, s27, 2
	v_lshl_add_u64 v[34:35], v[34:35], 0, s[36:37]
	global_store_dword v[34:35], v0, off offset:-128
	global_store_dword v[34:35], v36, off offset:-112

.LBB0_534:
	v_add_f32_e32 v0, v157, v158
	v_fmamk_f32 v0, v0, 0x3a000000, v240
	v_rsq_f32_e32 v0, v0
	v_add_u32_e32 v34, 0xa0, v150
	v_mad_i64_i32 v[40:41], s[16:17], v34, s3, v[152:153]
	v_pk_mul_f32 v[32:33], v[32:33], v[0:1] op_sel_hi:[1,0]
	v_pk_mul_f32 v[30:31], v[30:31], v[0:1] op_sel_hi:[1,0]
	v_pk_mul_f32 v[28:29], v[28:29], v[0:1] op_sel_hi:[1,0]
	v_pk_mul_f32 v[26:27], v[26:27], v[0:1] op_sel_hi:[1,0]
	v_cvt_pk_bf16_f32 v36, v30, v31
	v_cvt_pk_bf16_f32 v37, v32, v33
	v_pk_mul_f32 v[24:25], v[24:25], v[0:1] op_sel_hi:[1,0]
	v_cvt_pk_bf16_f32 v38, v26, v27
	v_cvt_pk_bf16_f32 v39, v28, v29
	v_pk_mul_f32 v[22:23], v[22:23], v[0:1] op_sel_hi:[1,0]
	v_pk_mul_f32 v[20:21], v[20:21], v[0:1] op_sel_hi:[1,0]
	v_pk_mul_f32 v[18:19], v[18:19], v[0:1] op_sel_hi:[1,0]
	s_and_b64 vcc, exec, s[8:9]
	global_store_dwordx4 v[40:41], v[36:39], off nt
	s_nop 1
	v_cvt_pk_bf16_f32 v36, v22, v23
	v_cvt_pk_bf16_f32 v37, v24, v25
	v_cvt_pk_bf16_f32 v38, v18, v19
	v_cvt_pk_bf16_f32 v39, v20, v21
	global_store_dwordx4 v[40:41], v[36:39], off offset:256 nt
	s_cbranch_vccnz .LBB0_538
	v_mul_f32_e32 v0, v31, v31
	v_mul_f32_e32 v27, v27, v27
	v_mul_f32_e32 v23, v23, v23
	v_mul_f32_e32 v19, v19, v19
	v_fmac_f32_e32 v0, v30, v30
	v_mul_f32_e32 v30, v33, v33
	v_fmac_f32_e32 v27, v26, v26
	v_mul_f32_e32 v26, v29, v29
	v_fmac_f32_e32 v23, v22, v22
	v_mul_f32_e32 v22, v25, v25
	v_fmac_f32_e32 v19, v18, v18
	v_mul_f32_e32 v18, v21, v21
	v_fmac_f32_e32 v30, v32, v32
	v_fmac_f32_e32 v26, v28, v28
	v_fmac_f32_e32 v22, v24, v24
	v_fmac_f32_e32 v18, v20, v20
	v_add_f32_e32 v0, v0, v30
	v_add_f32_e32 v26, v27, v26
	v_add_f32_e32 v22, v23, v22
	v_add_f32_e32 v18, v19, v18
	v_add_f32_e32 v0, v0, v26
	v_add_f32_e32 v19, v22, v18
	v_mov_b32_e32 v18, v0
	v_mov_b32_e32 v20, v19
	s_nop 0
	v_permlane16_swap_b32_e32 v0, v18
	v_permlane16_swap_b32_e32 v19, v20
	v_add_f32_e32 v0, v0, v18
	v_add_f32_e32 v19, v19, v20
	v_mov_b32_e32 v18, v0
	v_mov_b32_e32 v20, v19
	s_nop 0
	v_permlane32_swap_b32_e32 v0, v18
	v_permlane32_swap_b32_e32 v19, v20
	s_and_saveexec_b64 s[16:17], s[4:5]
	s_cbranch_execz .LBB0_537
	v_ashrrev_i32_e32 v35, 31, v34
	v_add_f32_e32 v20, v19, v20
	v_add_f32_e32 v0, v0, v18
	v_lshlrev_b64 v[18:19], 7, v[34:35]
	v_lshl_add_u64 v[18:19], v[138:139], 0, v[18:19]
	s_lshl_b32 s36, s2, 3
	s_mov_b32 s37, s40
	v_lshl_add_u64 v[18:19], s[36:37], 2, v[18:19]
	s_lshl_b32 s36, s27, 2
	v_lshl_add_u64 v[18:19], v[18:19], 0, s[36:37]
	global_store_dword v[18:19], v0, off offset:-128
	global_store_dword v[18:19], v20, off offset:-112

.LBB0_538:
	v_add_f32_e32 v0, v154, v155
	v_fmamk_f32 v0, v0, 0x3a000000, v240
	v_rsq_f32_e32 v0, v0
	v_add_u32_e32 v18, 0xb0, v150
	v_mad_i64_i32 v[26:27], s[16:17], v18, s3, v[152:153]
	v_pk_mul_f32 v[12:13], v[12:13], v[0:1] op_sel_hi:[1,0]
	v_pk_mul_f32 v[10:11], v[10:11], v[0:1] op_sel_hi:[1,0]
	v_pk_mul_f32 v[8:9], v[8:9], v[0:1] op_sel_hi:[1,0]
	v_cvt_pk_bf16_f32 v20, v10, v11
	v_cvt_pk_bf16_f32 v21, v12, v13
	v_pk_mul_f32 v[6:7], v[6:7], v[0:1] op_sel_hi:[1,0]
	v_pk_mul_f32 v[4:5], v[4:5], v[0:1] op_sel_hi:[1,0]
	v_cvt_pk_bf16_f32 v22, v6, v7
	v_cvt_pk_bf16_f32 v23, v8, v9
	global_store_dwordx4 v[26:27], v[20:23], off nt
	v_pk_mul_f32 v[14:15], v[14:15], v[0:1] op_sel_hi:[1,0]
	s_and_b64 vcc, exec, s[8:9]
	v_pk_mul_f32 v[20:21], v[2:3], v[0:1] op_sel_hi:[1,0]
	v_pk_mul_f32 v[2:3], v[16:17], v[0:1] op_sel_hi:[1,0]
	v_cvt_pk_bf16_f32 v22, v20, v21
	v_cvt_pk_bf16_f32 v23, v4, v5
	v_cvt_pk_bf16_f32 v24, v14, v15
	s_nop 0
	v_cvt_pk_bf16_f32 v25, v2, v3
	global_store_dwordx4 v[26:27], v[22:25], off offset:256 nt
	s_cbranch_vccnz .LBB0_542
	v_mul_f32_e32 v0, v11, v11
	v_mul_f32_e32 v7, v7, v7
	v_fmac_f32_e32 v0, v10, v10
	v_mul_f32_e32 v10, v13, v13
	v_fmac_f32_e32 v7, v6, v6
	v_mul_f32_e32 v6, v9, v9
	v_fmac_f32_e32 v10, v12, v12
	v_fmac_f32_e32 v6, v8, v8
	v_add_f32_e32 v0, v0, v10
	v_add_f32_e32 v6, v7, v6
	v_add_f32_e32 v0, v0, v6
	v_mul_f32_e32 v6, v21, v21
	v_mul_f32_e32 v5, v5, v5
	v_fmac_f32_e32 v6, v20, v20
	v_fmac_f32_e32 v5, v4, v4
	v_add_f32_e32 v4, v6, v5
	v_mul_f32_e32 v5, v15, v15
	v_mul_f32_e32 v3, v3, v3
	v_fmac_f32_e32 v5, v14, v14
	v_fmac_f32_e32 v3, v2, v2
	v_add_f32_e32 v2, v5, v3
	v_add_f32_e32 v3, v4, v2
	v_mov_b32_e32 v2, v0
	v_mov_b32_e32 v4, v3
	s_nop 0
	v_permlane16_swap_b32_e32 v0, v2
	v_permlane16_swap_b32_e32 v3, v4
	v_add_f32_e32 v0, v0, v2
	v_add_f32_e32 v3, v3, v4
	v_mov_b32_e32 v2, v0
	v_mov_b32_e32 v4, v3
	s_nop 0
	v_permlane32_swap_b32_e32 v0, v2
	v_permlane32_swap_b32_e32 v3, v4
	s_and_saveexec_b64 s[8:9], s[4:5]
	s_cbranch_execz .LBB0_541
	v_ashrrev_i32_e32 v19, 31, v18
	v_add_f32_e32 v4, v3, v4
	v_add_f32_e32 v0, v0, v2
	v_lshlrev_b64 v[2:3], 7, v[18:19]
	v_lshl_add_u64 v[2:3], v[138:139], 0, v[2:3]
	s_lshl_b32 s2, s2, 3
	s_mov_b32 s3, s40
	v_lshl_add_u64 v[2:3], s[2:3], 2, v[2:3]
	s_lshl_b32 s2, s27, 2
	v_lshl_add_u64 v[2:3], v[2:3], 0, s[2:3]
	global_store_dword v[2:3], v0, off offset:-128
	global_store_dword v[2:3], v4, off offset:-112

.Lalign_skip_2:
	v_add_f32_e32 v149, v149, v151
	v_lshlrev_b32_e32 v151, 16, v173
	v_and_b32_e32 v153, 0xffff0000, v173
	v_add_f32_e32 v151, v151, v153
	v_add_f32_e32 v149, v149, v151
	v_lshlrev_b32_e32 v151, 16, v174
	v_and_b32_e32 v153, 0xffff0000, v174
	v_add_f32_e32 v151, v151, v153
	v_lshlrev_b32_e32 v153, 16, v175
	v_and_b32_e32 v154, 0xffff0000, v175
	v_add_f32_e32 v153, v153, v154
	v_add_f32_e32 v151, v151, v153
	v_add_f32_e32 v149, v149, v151
	v_mov_b32_e32 v151, v149
	s_nop 1
	v_permlane16_swap_b32_e32 v149, v151
	v_add_f32_e32 v149, v149, v151
	ds_read_b128 v[172:175], v170 offset:9216
	v_mov_b32_e32 v151, v149
	s_nop 1
	v_permlane32_swap_b32_e32 v149, v151
	v_add_f32_e32 v149, v149, v151
	v_fmamk_f32 v149, v149, 0x3a000000, v240
	v_rsq_f32_e32 v154, v149
	s_waitcnt lgkmcnt(0)
	v_lshlrev_b32_e32 v149, 16, v172
	v_and_b32_e32 v151, 0xffff0000, v172
	v_add_f32_e32 v149, v149, v151
	v_lshlrev_b32_e32 v151, 16, v173
	v_and_b32_e32 v153, 0xffff0000, v173
	v_add_f32_e32 v151, v151, v153
	v_add_f32_e32 v149, v149, v151
	v_lshlrev_b32_e32 v151, 16, v174
	v_and_b32_e32 v153, 0xffff0000, v174
	v_add_f32_e32 v151, v151, v153
	v_lshlrev_b32_e32 v153, 16, v175
	v_and_b32_e32 v155, 0xffff0000, v175
	v_add_f32_e32 v153, v153, v155
	v_add_f32_e32 v151, v151, v153
	v_add_f32_e32 v149, v149, v151
	v_mov_b32_e32 v151, v149
	s_nop 1
	v_permlane16_swap_b32_e32 v149, v151
	v_add_f32_e32 v149, v149, v151
	ds_read_b128 v[172:175], v170 offset:10240
	v_mov_b32_e32 v151, v149
	s_nop 1
	v_permlane32_swap_b32_e32 v149, v151
	v_add_f32_e32 v149, v149, v151
	v_fmamk_f32 v149, v149, 0x3a000000, v240
	v_rsq_f32_e32 v160, v149
	s_waitcnt lgkmcnt(0)
	v_lshlrev_b32_e32 v149, 16, v172
	v_and_b32_e32 v151, 0xffff0000, v172
	v_add_f32_e32 v149, v149, v151
	v_lshlrev_b32_e32 v151, 16, v173
	v_and_b32_e32 v153, 0xffff0000, v173
	v_add_f32_e32 v151, v151, v153
	v_add_f32_e32 v149, v149, v151
	v_lshlrev_b32_e32 v151, 16, v174
	v_and_b32_e32 v153, 0xffff0000, v174
	v_add_f32_e32 v151, v151, v153
	v_lshlrev_b32_e32 v153, 16, v175
	v_and_b32_e32 v155, 0xffff0000, v175
	v_add_f32_e32 v153, v153, v155
	v_add_f32_e32 v151, v151, v153
	v_add_f32_e32 v149, v149, v151
	v_mov_b32_e32 v151, v149
	s_nop 1
	v_permlane16_swap_b32_e32 v149, v151
	v_add_f32_e32 v149, v149, v151
	ds_read_b128 v[172:175], v170 offset:11264
	v_mov_b32_e32 v151, v149
	s_nop 1
	v_permlane32_swap_b32_e32 v149, v151
	v_add_f32_e32 v149, v149, v151
	v_fmamk_f32 v149, v149, 0x3a000000, v240
	v_rsq_f32_e32 v158, v149
	s_waitcnt lgkmcnt(0)
	v_lshlrev_b32_e32 v149, 16, v172
	v_and_b32_e32 v151, 0xffff0000, v172
	v_add_f32_e32 v149, v149, v151
	v_lshlrev_b32_e32 v151, 16, v173
	v_and_b32_e32 v153, 0xffff0000, v173
	v_add_f32_e32 v151, v151, v153
	v_add_f32_e32 v149, v149, v151
	v_lshlrev_b32_e32 v151, 16, v174
	v_and_b32_e32 v153, 0xffff0000, v174
	v_add_f32_e32 v151, v151, v153
	v_lshlrev_b32_e32 v153, 16, v175
	v_and_b32_e32 v155, 0xffff0000, v175
	v_add_f32_e32 v153, v153, v155
	v_add_f32_e32 v151, v151, v153
	v_add_f32_e32 v149, v149, v151
	v_mov_b32_e32 v151, v149
	v_fmamk_f32 v0, v0, 0x3a000000, v240
	s_nop 0
	v_permlane16_swap_b32_e32 v149, v151
	v_rsq_f32_e32 v0, v0
	v_add_f32_e32 v149, v149, v151
	v_mov_b32_e32 v151, v149
	s_nop 1
	v_permlane32_swap_b32_e32 v149, v151
	v_add_f32_e32 v149, v149, v151
	v_fmamk_f32 v149, v149, 0x3a000000, v240
	v_pk_mul_f32 v[122:123], v[122:123], v[0:1] op_sel_hi:[1,0]
	v_rsq_f32_e32 v162, v149
	v_ashrrev_i32_e32 v149, 31, v148
	v_max_f32_e32 v122, 0, v122
	v_lshl_add_u64 v[172:173], v[164:165], 1, v[138:139]
	v_lshlrev_b64 v[164:165], 14, v[148:149]
	v_pk_mul_f32 v[124:125], v[124:125], v[0:1] op_sel_hi:[1,0]
	v_mul_f32_e32 v149, v122, v122
	v_max_f32_e32 v122, 0, v123
	v_pk_mul_f32 v[126:127], v[126:127], v[0:1] op_sel_hi:[1,0]
	v_mul_f32_e32 v151, v122, v122
	v_max_f32_e32 v122, 0, v124
	v_pk_mul_f32 v[114:115], v[114:115], v[0:1] op_sel_hi:[1,0]
	v_pk_mul_f32 v[128:129], v[128:129], v[0:1] op_sel_hi:[1,0]
	v_max_f32_e32 v126, 0, v126
	v_max_f32_e32 v127, 0, v127
	v_mul_f32_e32 v153, v122, v122
	v_max_f32_e32 v122, 0, v125
	v_pk_mul_f32 v[120:121], v[120:121], v[0:1] op_sel_hi:[1,0]
	v_pk_mul_f32 v[118:119], v[118:119], v[0:1] op_sel_hi:[1,0]
	v_max_f32_e32 v114, 0, v114
	v_lshl_add_u64 v[164:165], v[172:173], 0, v[164:165]
	v_mul_f32_e32 v126, v126, v126
	v_mul_f32_e32 v127, v127, v127
	v_max_f32_e32 v128, 0, v128
	v_max_f32_e32 v129, 0, v129
	v_mul_f32_e32 v125, v122, v122
	v_cvt_pk_bf16_f32 v122, v126, v127
	v_pk_mul_f32 v[116:117], v[116:117], v[0:1] op_sel_hi:[1,0]
	v_max_f32_e32 v0, 0, v118
	v_max_f32_e32 v118, 0, v119
	v_max_f32_e32 v119, 0, v120
	v_max_f32_e32 v120, 0, v121
	v_mul_f32_e32 v121, v114, v114
	v_max_f32_e32 v114, 0, v115
	v_mul_f32_e32 v128, v128, v128
	v_mul_f32_e32 v129, v129, v129
	v_cvt_pk_bf16_f32 v123, v128, v129
	v_cvt_pk_bf16_f32 v124, v149, v151
	v_cvt_pk_bf16_f32 v125, v153, v125
	global_store_dwordx4 v[164:165], v[122:125], off nt
	v_pk_mul_f32 v[106:107], v[106:107], v[152:153] op_sel_hi:[1,0]
	v_mul_f32_e32 v0, v0, v0
	v_mul_f32_e32 v122, v114, v114
	v_max_f32_e32 v114, 0, v116
	v_mul_f32_e32 v123, v114, v114
	v_max_f32_e32 v114, 0, v117
	v_mul_f32_e32 v118, v118, v118
	v_mul_f32_e32 v117, v114, v114
	v_cvt_pk_bf16_f32 v114, v0, v118
	v_pk_mul_f32 v[112:113], v[112:113], v[152:153] op_sel_hi:[1,0]
	v_pk_mul_f32 v[110:111], v[110:111], v[152:153] op_sel_hi:[1,0]
	v_max_f32_e32 v106, 0, v106
	v_mul_f32_e32 v119, v119, v119
	v_mul_f32_e32 v120, v120, v120
	v_cvt_pk_bf16_f32 v115, v119, v120
	v_cvt_pk_bf16_f32 v116, v121, v122
	v_cvt_pk_bf16_f32 v117, v123, v117
	global_store_dwordx4 v[164:165], v[114:117], off offset:256 nt
	v_pk_mul_f32 v[108:109], v[108:109], v[152:153] op_sel_hi:[1,0]
	v_max_f32_e32 v0, 0, v110
	v_or_b32_e32 v114, 16, v148
	v_max_f32_e32 v110, 0, v111
	v_max_f32_e32 v111, 0, v112
	v_max_f32_e32 v112, 0, v113
	v_mul_f32_e32 v113, v106, v106
	v_max_f32_e32 v106, 0, v107
	v_ashrrev_i32_e32 v115, 31, v114
	v_mul_f32_e32 v116, v106, v106
	v_max_f32_e32 v106, 0, v108
	v_pk_mul_f32 v[98:99], v[98:99], v[152:153] op_sel_hi:[1,0]
	v_lshlrev_b64 v[114:115], 14, v[114:115]
	v_mul_f32_e32 v0, v0, v0
	v_mul_f32_e32 v117, v106, v106
	v_max_f32_e32 v106, 0, v109
	v_pk_mul_f32 v[104:105], v[104:105], v[152:153] op_sel_hi:[1,0]
	v_pk_mul_f32 v[102:103], v[102:103], v[152:153] op_sel_hi:[1,0]
	v_max_f32_e32 v98, 0, v98
	v_lshl_add_u64 v[114:115], v[172:173], 0, v[114:115]
	v_mul_f32_e32 v110, v110, v110
	v_mul_f32_e32 v109, v106, v106
	v_cvt_pk_bf16_f32 v106, v0, v110
	v_pk_mul_f32 v[100:101], v[100:101], v[152:153] op_sel_hi:[1,0]
	v_max_f32_e32 v0, 0, v102
	v_max_f32_e32 v102, 0, v103
	v_max_f32_e32 v103, 0, v104
	v_max_f32_e32 v104, 0, v105
	v_mul_f32_e32 v105, v98, v98
	v_max_f32_e32 v98, 0, v99
	v_mul_f32_e32 v111, v111, v111
	v_mul_f32_e32 v112, v112, v112
	v_cvt_pk_bf16_f32 v107, v111, v112
	v_cvt_pk_bf16_f32 v108, v113, v116
	v_cvt_pk_bf16_f32 v109, v117, v109
	global_store_dwordx4 v[114:115], v[106:109], off nt
	v_pk_mul_f32 v[90:91], v[90:91], v[150:151] op_sel_hi:[1,0]
	v_mul_f32_e32 v0, v0, v0
	v_mul_f32_e32 v106, v98, v98
	v_max_f32_e32 v98, 0, v100
	v_mul_f32_e32 v107, v98, v98
	v_max_f32_e32 v98, 0, v101
	v_mul_f32_e32 v102, v102, v102
	v_mul_f32_e32 v101, v98, v98
	v_cvt_pk_bf16_f32 v98, v0, v102
	v_pk_mul_f32 v[96:97], v[96:97], v[150:151] op_sel_hi:[1,0]
	v_pk_mul_f32 v[94:95], v[94:95], v[150:151] op_sel_hi:[1,0]
	v_max_f32_e32 v90, 0, v90
	v_mul_f32_e32 v103, v103, v103
	v_mul_f32_e32 v104, v104, v104
	v_cvt_pk_bf16_f32 v99, v103, v104
	v_cvt_pk_bf16_f32 v100, v105, v106
	v_cvt_pk_bf16_f32 v101, v107, v101
	global_store_dwordx4 v[114:115], v[98:101], off offset:256 nt
	v_pk_mul_f32 v[92:93], v[92:93], v[150:151] op_sel_hi:[1,0]
	v_max_f32_e32 v0, 0, v94
	v_or_b32_e32 v98, 32, v148
	v_max_f32_e32 v94, 0, v95
	v_max_f32_e32 v95, 0, v96
	v_max_f32_e32 v96, 0, v97
	v_mul_f32_e32 v97, v90, v90
	v_max_f32_e32 v90, 0, v91
	v_ashrrev_i32_e32 v99, 31, v98
	v_mul_f32_e32 v100, v90, v90
	v_max_f32_e32 v90, 0, v92
	v_pk_mul_f32 v[82:83], v[82:83], v[150:151] op_sel_hi:[1,0]
	v_lshlrev_b64 v[98:99], 14, v[98:99]
	v_mul_f32_e32 v0, v0, v0
	v_mul_f32_e32 v101, v90, v90
	v_max_f32_e32 v90, 0, v93
	v_pk_mul_f32 v[88:89], v[88:89], v[150:151] op_sel_hi:[1,0]
	v_pk_mul_f32 v[86:87], v[86:87], v[150:151] op_sel_hi:[1,0]
	v_max_f32_e32 v82, 0, v82
	v_lshl_add_u64 v[98:99], v[172:173], 0, v[98:99]
	v_mul_f32_e32 v94, v94, v94
	v_mul_f32_e32 v93, v90, v90
	v_cvt_pk_bf16_f32 v90, v0, v94
	v_pk_mul_f32 v[84:85], v[84:85], v[150:151] op_sel_hi:[1,0]
	v_max_f32_e32 v0, 0, v86
	v_max_f32_e32 v86, 0, v87
	v_max_f32_e32 v87, 0, v88
	v_max_f32_e32 v88, 0, v89
	v_mul_f32_e32 v89, v82, v82
	v_max_f32_e32 v82, 0, v83
	v_mul_f32_e32 v95, v95, v95
	v_mul_f32_e32 v96, v96, v96
	v_cvt_pk_bf16_f32 v91, v95, v96
	v_cvt_pk_bf16_f32 v92, v97, v100
	v_cvt_pk_bf16_f32 v93, v101, v93
	global_store_dwordx4 v[98:99], v[90:93], off nt
	v_pk_mul_f32 v[74:75], v[74:75], v[156:157] op_sel_hi:[1,0]
	v_mul_f32_e32 v0, v0, v0
	v_mul_f32_e32 v90, v82, v82
	v_max_f32_e32 v82, 0, v84
	v_mul_f32_e32 v91, v82, v82
	v_max_f32_e32 v82, 0, v85
	v_mul_f32_e32 v86, v86, v86
	v_mul_f32_e32 v85, v82, v82
	v_cvt_pk_bf16_f32 v82, v0, v86
	v_pk_mul_f32 v[80:81], v[80:81], v[156:157] op_sel_hi:[1,0]
	v_pk_mul_f32 v[78:79], v[78:79], v[156:157] op_sel_hi:[1,0]
	v_max_f32_e32 v74, 0, v74
	v_mul_f32_e32 v87, v87, v87
	v_mul_f32_e32 v88, v88, v88
	v_cvt_pk_bf16_f32 v83, v87, v88
	v_cvt_pk_bf16_f32 v84, v89, v90
	v_cvt_pk_bf16_f32 v85, v91, v85
	global_store_dwordx4 v[98:99], v[82:85], off offset:256 nt
	v_pk_mul_f32 v[76:77], v[76:77], v[156:157] op_sel_hi:[1,0]
	v_max_f32_e32 v0, 0, v78
	v_or_b32_e32 v82, 48, v148
	v_max_f32_e32 v78, 0, v79
	v_max_f32_e32 v79, 0, v80
	v_max_f32_e32 v80, 0, v81
	v_mul_f32_e32 v81, v74, v74
	v_max_f32_e32 v74, 0, v75
	v_ashrrev_i32_e32 v83, 31, v82
	v_mul_f32_e32 v84, v74, v74
	v_max_f32_e32 v74, 0, v76
	v_pk_mul_f32 v[66:67], v[66:67], v[156:157] op_sel_hi:[1,0]
	v_lshlrev_b64 v[82:83], 14, v[82:83]
	v_mul_f32_e32 v0, v0, v0
	v_mul_f32_e32 v85, v74, v74
	v_max_f32_e32 v74, 0, v77
	v_pk_mul_f32 v[72:73], v[72:73], v[156:157] op_sel_hi:[1,0]
	v_pk_mul_f32 v[70:71], v[70:71], v[156:157] op_sel_hi:[1,0]
	v_max_f32_e32 v66, 0, v66
	v_lshl_add_u64 v[82:83], v[172:173], 0, v[82:83]
	v_mul_f32_e32 v78, v78, v78
	v_mul_f32_e32 v77, v74, v74
	v_cvt_pk_bf16_f32 v74, v0, v78
	v_pk_mul_f32 v[68:69], v[68:69], v[156:157] op_sel_hi:[1,0]
	v_max_f32_e32 v0, 0, v70
	v_max_f32_e32 v70, 0, v71
	v_max_f32_e32 v71, 0, v72
	v_max_f32_e32 v72, 0, v73
	v_mul_f32_e32 v73, v66, v66
	v_max_f32_e32 v66, 0, v67
	v_mul_f32_e32 v79, v79, v79
	v_mul_f32_e32 v80, v80, v80
	v_cvt_pk_bf16_f32 v75, v79, v80
	v_cvt_pk_bf16_f32 v76, v81, v84
	v_cvt_pk_bf16_f32 v77, v85, v77
	global_store_dwordx4 v[82:83], v[74:77], off nt
	v_pk_mul_f32 v[58:59], v[58:59], v[154:155] op_sel_hi:[1,0]
	v_mul_f32_e32 v0, v0, v0
	v_mul_f32_e32 v74, v66, v66
	v_max_f32_e32 v66, 0, v68
	v_mul_f32_e32 v75, v66, v66
	v_max_f32_e32 v66, 0, v69
	v_pk_mul_f32 v[64:65], v[64:65], v[154:155] op_sel_hi:[1,0]
	v_pk_mul_f32 v[62:63], v[62:63], v[154:155] op_sel_hi:[1,0]
	v_max_f32_e32 v58, 0, v58
	v_mul_f32_e32 v70, v70, v70
	v_mul_f32_e32 v71, v71, v71
	v_mul_f32_e32 v72, v72, v72
	v_mul_f32_e32 v69, v66, v66
	v_cvt_pk_bf16_f32 v66, v0, v70
	v_cvt_pk_bf16_f32 v67, v71, v72
	v_cvt_pk_bf16_f32 v68, v73, v74
	v_pk_mul_f32 v[60:61], v[60:61], v[154:155] op_sel_hi:[1,0]
	v_max_f32_e32 v0, 0, v62
	v_max_f32_e32 v62, 0, v63
	v_max_f32_e32 v63, 0, v64
	v_max_f32_e32 v64, 0, v65
	v_mul_f32_e32 v65, v58, v58
	v_max_f32_e32 v58, 0, v59
	v_cvt_pk_bf16_f32 v69, v75, v69
	global_store_dwordx4 v[82:83], v[66:69], off offset:256 nt
	v_mul_f32_e32 v62, v62, v62
	s_mov_b32 s7, 0x200000
	v_mul_f32_e32 v68, v58, v58
	v_max_f32_e32 v58, 0, v60
	v_mul_f32_e32 v69, v58, v58
	v_max_f32_e32 v58, 0, v61
	v_pk_mul_f32 v[50:51], v[50:51], v[154:155] op_sel_hi:[1,0]
	v_mul_f32_e32 v0, v0, v0
	v_mul_f32_e32 v63, v63, v63
	v_mul_f32_e32 v61, v58, v58
	v_cvt_pk_bf16_f32 v58, v0, v62
	v_add_co_u32_e32 v62, vcc, s7, v164
	v_pk_mul_f32 v[56:57], v[56:57], v[154:155] op_sel_hi:[1,0]
	v_pk_mul_f32 v[54:55], v[54:55], v[154:155] op_sel_hi:[1,0]
	v_max_f32_e32 v50, 0, v50
	v_mul_f32_e32 v64, v64, v64
	v_cvt_pk_bf16_f32 v59, v63, v64
	v_addc_co_u32_e32 v63, vcc, 0, v165, vcc
	v_pk_mul_f32 v[52:53], v[52:53], v[154:155] op_sel_hi:[1,0]
	v_max_f32_e32 v0, 0, v54
	v_max_f32_e32 v54, 0, v55
	v_max_f32_e32 v55, 0, v56
	v_max_f32_e32 v56, 0, v57
	v_mul_f32_e32 v57, v50, v50
	v_max_f32_e32 v50, 0, v51
	v_cvt_pk_bf16_f32 v60, v65, v68
	v_cvt_pk_bf16_f32 v61, v69, v61
	global_store_dwordx4 v[62:63], v[58:61], off nt
	v_pk_mul_f32 v[42:43], v[42:43], v[160:161] op_sel_hi:[1,0]
	v_mul_f32_e32 v0, v0, v0
	v_mul_f32_e32 v58, v50, v50
	v_max_f32_e32 v50, 0, v52
	v_mul_f32_e32 v59, v50, v50
	v_max_f32_e32 v50, 0, v53
	v_pk_mul_f32 v[48:49], v[48:49], v[160:161] op_sel_hi:[1,0]
	v_pk_mul_f32 v[46:47], v[46:47], v[160:161] op_sel_hi:[1,0]
	v_max_f32_e32 v42, 0, v42
	v_lshl_add_u64 v[66:67], v[164:165], 0, s[50:51]
	v_mul_f32_e32 v54, v54, v54
	v_mul_f32_e32 v55, v55, v55
	v_mul_f32_e32 v56, v56, v56
	v_mul_f32_e32 v53, v50, v50
	v_cvt_pk_bf16_f32 v50, v0, v54
	v_cvt_pk_bf16_f32 v51, v55, v56
	v_cvt_pk_bf16_f32 v52, v57, v58
	v_pk_mul_f32 v[44:45], v[44:45], v[160:161] op_sel_hi:[1,0]
	v_max_f32_e32 v0, 0, v46
	v_max_f32_e32 v46, 0, v47
	v_max_f32_e32 v47, 0, v48
	v_max_f32_e32 v48, 0, v49
	v_mul_f32_e32 v49, v42, v42
	v_max_f32_e32 v42, 0, v43
	v_cvt_pk_bf16_f32 v53, v59, v53
	global_store_dwordx4 v[66:67], v[50:53], off offset:256 nt
	v_mul_f32_e32 v46, v46, v46
	s_mov_b32 s7, 0x240000
	v_mul_f32_e32 v52, v42, v42
	v_max_f32_e32 v42, 0, v44
	v_mul_f32_e32 v53, v42, v42
	v_max_f32_e32 v42, 0, v45
	v_pk_mul_f32 v[34:35], v[34:35], v[160:161] op_sel_hi:[1,0]
	v_mul_f32_e32 v0, v0, v0
	v_mul_f32_e32 v47, v47, v47
	v_mul_f32_e32 v45, v42, v42
	v_cvt_pk_bf16_f32 v42, v0, v46
	v_add_co_u32_e32 v46, vcc, s7, v164
	v_pk_mul_f32 v[40:41], v[40:41], v[160:161] op_sel_hi:[1,0]
	v_pk_mul_f32 v[38:39], v[38:39], v[160:161] op_sel_hi:[1,0]
	v_max_f32_e32 v34, 0, v34
	v_mul_f32_e32 v48, v48, v48
	v_cvt_pk_bf16_f32 v43, v47, v48
	v_addc_co_u32_e32 v47, vcc, 0, v165, vcc
	v_pk_mul_f32 v[36:37], v[36:37], v[160:161] op_sel_hi:[1,0]
	v_max_f32_e32 v0, 0, v38
	v_max_f32_e32 v38, 0, v39
	v_max_f32_e32 v39, 0, v40
	v_max_f32_e32 v40, 0, v41
	v_mul_f32_e32 v41, v34, v34
	v_max_f32_e32 v34, 0, v35
	v_cvt_pk_bf16_f32 v44, v49, v52
	v_cvt_pk_bf16_f32 v45, v53, v45
	global_store_dwordx4 v[46:47], v[42:45], off nt
	v_pk_mul_f32 v[26:27], v[26:27], v[158:159] op_sel_hi:[1,0]
	s_mov_b64 s[10:11], 0x240000
	v_mul_f32_e32 v42, v34, v34
	v_max_f32_e32 v34, 0, v36
	v_mul_f32_e32 v0, v0, v0
	v_mul_f32_e32 v43, v34, v34
	v_max_f32_e32 v34, 0, v37
	v_pk_mul_f32 v[32:33], v[32:33], v[158:159] op_sel_hi:[1,0]
	v_pk_mul_f32 v[30:31], v[30:31], v[158:159] op_sel_hi:[1,0]
	v_max_f32_e32 v26, 0, v26
	v_lshl_add_u64 v[50:51], v[164:165], 0, s[10:11]
	v_mul_f32_e32 v38, v38, v38
	v_mul_f32_e32 v39, v39, v39
	v_mul_f32_e32 v40, v40, v40
	v_mul_f32_e32 v37, v34, v34
	v_cvt_pk_bf16_f32 v34, v0, v38
	v_cvt_pk_bf16_f32 v35, v39, v40
	v_cvt_pk_bf16_f32 v36, v41, v42
	v_pk_mul_f32 v[28:29], v[28:29], v[158:159] op_sel_hi:[1,0]
	v_max_f32_e32 v0, 0, v30
	v_max_f32_e32 v30, 0, v31
	v_max_f32_e32 v31, 0, v32
	v_max_f32_e32 v32, 0, v33
	v_mul_f32_e32 v33, v26, v26
	v_max_f32_e32 v26, 0, v27
	v_cvt_pk_bf16_f32 v37, v43, v37
	global_store_dwordx4 v[50:51], v[34:37], off offset:256 nt
	v_mul_f32_e32 v30, v30, v30
	s_mov_b32 s7, 0x280000
	v_mul_f32_e32 v36, v26, v26
	v_max_f32_e32 v26, 0, v28
	v_mul_f32_e32 v37, v26, v26
	v_max_f32_e32 v26, 0, v29
	v_pk_mul_f32 v[18:19], v[18:19], v[158:159] op_sel_hi:[1,0]
	v_mul_f32_e32 v0, v0, v0
	v_mul_f32_e32 v31, v31, v31
	v_mul_f32_e32 v29, v26, v26
	v_cvt_pk_bf16_f32 v26, v0, v30
	v_add_co_u32_e32 v30, vcc, s7, v164
	v_pk_mul_f32 v[24:25], v[24:25], v[158:159] op_sel_hi:[1,0]
	v_pk_mul_f32 v[22:23], v[22:23], v[158:159] op_sel_hi:[1,0]
	v_max_f32_e32 v18, 0, v18
	v_mul_f32_e32 v32, v32, v32
	v_cvt_pk_bf16_f32 v27, v31, v32
	v_addc_co_u32_e32 v31, vcc, 0, v165, vcc
	v_pk_mul_f32 v[20:21], v[20:21], v[158:159] op_sel_hi:[1,0]
	v_max_f32_e32 v0, 0, v22
	v_max_f32_e32 v22, 0, v23
	v_max_f32_e32 v23, 0, v24
	v_max_f32_e32 v24, 0, v25
	v_mul_f32_e32 v25, v18, v18
	v_max_f32_e32 v18, 0, v19
	v_cvt_pk_bf16_f32 v28, v33, v36
	v_cvt_pk_bf16_f32 v29, v37, v29
	global_store_dwordx4 v[30:31], v[26:29], off nt
	v_pk_mul_f32 v[10:11], v[10:11], v[162:163] op_sel_hi:[1,0]
	s_mov_b64 s[10:11], 0x280000
	v_mul_f32_e32 v26, v18, v18
	v_max_f32_e32 v18, 0, v20
	v_mul_f32_e32 v0, v0, v0
	v_mul_f32_e32 v27, v18, v18
	v_max_f32_e32 v18, 0, v21
	v_pk_mul_f32 v[16:17], v[16:17], v[162:163] op_sel_hi:[1,0]
	v_pk_mul_f32 v[14:15], v[14:15], v[162:163] op_sel_hi:[1,0]
	v_max_f32_e32 v10, 0, v10
	v_lshl_add_u64 v[34:35], v[164:165], 0, s[10:11]
	v_mul_f32_e32 v22, v22, v22
	v_mul_f32_e32 v23, v23, v23
	v_mul_f32_e32 v24, v24, v24
	v_mul_f32_e32 v21, v18, v18
	v_cvt_pk_bf16_f32 v18, v0, v22
	v_cvt_pk_bf16_f32 v19, v23, v24
	v_cvt_pk_bf16_f32 v20, v25, v26
	v_pk_mul_f32 v[12:13], v[12:13], v[162:163] op_sel_hi:[1,0]
	v_max_f32_e32 v0, 0, v14
	v_max_f32_e32 v14, 0, v15
	v_max_f32_e32 v15, 0, v16
	v_max_f32_e32 v16, 0, v17
	v_mul_f32_e32 v17, v10, v10
	v_max_f32_e32 v10, 0, v11
	v_cvt_pk_bf16_f32 v21, v27, v21
	global_store_dwordx4 v[34:35], v[18:21], off offset:256 nt
	v_mul_f32_e32 v0, v0, v0
	v_mul_f32_e32 v14, v14, v14
	v_mul_f32_e32 v20, v10, v10
	v_max_f32_e32 v10, 0, v12
	v_mul_f32_e32 v21, v10, v10
	v_max_f32_e32 v10, 0, v13
	s_mov_b32 s7, 0x2c0000
	v_pk_mul_f32 v[4:5], v[4:5], v[162:163] op_sel_hi:[1,0]
	v_pk_mul_f32 v[2:3], v[2:3], v[162:163] op_sel_hi:[1,0]
	v_pk_mul_f32 v[6:7], v[6:7], v[162:163] op_sel_hi:[1,0]
	v_mul_f32_e32 v15, v15, v15
	v_mul_f32_e32 v13, v10, v10
	v_cvt_pk_bf16_f32 v10, v0, v14
	v_add_co_u32_e32 v14, vcc, s7, v164
	v_pk_mul_f32 v[8:9], v[8:9], v[162:163] op_sel_hi:[1,0]
	v_max_f32_e32 v0, 0, v2
	v_max_f32_e32 v2, 0, v3
	v_max_f32_e32 v3, 0, v4
	v_max_f32_e32 v4, 0, v5
	v_max_f32_e32 v5, 0, v6
	s_mov_b64 s[10:11], 0x2c0000
	v_mul_f32_e32 v16, v16, v16
	v_cvt_pk_bf16_f32 v11, v15, v16
	v_addc_co_u32_e32 v15, vcc, 0, v165, vcc
	v_mul_f32_e32 v2, v2, v2
	v_mul_f32_e32 v3, v3, v3
	v_mul_f32_e32 v4, v4, v4
	v_mul_f32_e32 v5, v5, v5
	v_max_f32_e32 v6, 0, v7
	v_max_f32_e32 v7, 0, v8
	v_max_f32_e32 v8, 0, v9
	v_lshl_add_u64 v[18:19], v[164:165], 0, s[10:11]
	v_cvt_pk_bf16_f32 v12, v17, v20
	v_cvt_pk_bf16_f32 v13, v21, v13
	global_store_dwordx4 v[14:15], v[10:13], off nt
	v_mul_f32_e32 v0, v0, v0
	v_mul_f32_e32 v6, v6, v6
	v_mul_f32_e32 v7, v7, v7
	v_mul_f32_e32 v8, v8, v8
	v_cvt_pk_bf16_f32 v2, v0, v2
	v_cvt_pk_bf16_f32 v3, v3, v4
	v_cvt_pk_bf16_f32 v4, v5, v6
	v_cvt_pk_bf16_f32 v5, v7, v8
	s_mov_b64 s[10:11], -1
	s_andn2_b64 vcc, exec, s[4:5]
	global_store_dwordx4 v[18:19], v[2:5], off offset:256 nt
	s_cbranch_vccnz .LBB0_1160
	s_andn2_b64 vcc, exec, s[0:1]
	s_cbranch_vccnz .LBB0_1159
	s_barrier
	s_branch .LBB0_1159
